# E30: u64->f32 statistic conversion chains (64-bit shift/min/or/ldexp identities) reduced to mov+cvt at 17 sites (13 of 16 SwiGLU); on E28
# speedup vs baseline: 1.0039x; 1.0039x over previous
.LBB0_307:
	s_lshl_b32 s8, s93, 8
	s_add_i32 s8, s8, s46
	s_ashr_i32 s9, s8, 31
	v_lshl_add_u64 v[142:143], s[8:9], 3, v[130:131]
	global_load_dwordx2 v[144:145], v[142:143], off
	global_load_dwordx2 v[154:155], v[142:143], off offset:128
	v_pk_mul_f32 v[156:157], v[114:115], v[126:127]
	v_pk_mul_f32 v[170:171], v[112:113], v[124:125]
	v_pk_mul_f32 v[172:173], v[110:111], v[122:123]
	v_pk_mul_f32 v[174:175], v[108:109], v[120:121]
	v_pk_mul_f32 v[176:177], v[106:107], v[118:119]
	global_load_dwordx2 v[178:179], v[142:143], off offset:256
	global_load_dwordx2 v[126:127], v[142:143], off offset:384
	global_load_dwordx2 v[124:125], v[142:143], off offset:1024
	global_load_dwordx2 v[122:123], v[142:143], off offset:1152
	global_load_dwordx2 v[120:121], v[142:143], off offset:1280
	global_load_dwordx2 v[118:119], v[142:143], off offset:1408
	s_flbit_i32_b32 s8, 0
	s_min_u32 s42, s8, 32
	s_mul_i32 s8, s93, 0x58
	s_sub_i32 s93, 32, s42
	v_pk_mul_f32 v[128:129], v[116:117], v[128:129]
	s_lshl_b32 s9, s92, 1
	s_or_b32 s9, s9, s73
	s_add_i32 s8, s9, s8
	s_ashr_i32 s9, s8, 31
	s_lshl_b64 s[8:9], s[8:9], 15
	s_add_u32 s43, s25, s8
	s_addc_u32 s92, s30, s9
	s_add_u32 s8, s43, s64
	s_addc_u32 s9, s92, s65
	s_add_u32 s8, s8, s88
	s_addc_u32 s9, s9, 0
	v_pk_mul_f32 v[98:99], v[102:103], v[98:99]
	v_pk_mul_f32 v[100:101], v[104:105], v[100:101]
	v_pk_mul_f32 v[90:91], v[94:95], v[90:91]
	v_pk_mul_f32 v[92:93], v[96:97], v[92:93]
	v_pk_mul_f32 v[82:83], v[86:87], v[82:83]
	v_pk_mul_f32 v[84:85], v[88:89], v[84:85]
	v_pk_mul_f32 v[74:75], v[78:79], v[74:75]
	v_pk_mul_f32 v[76:77], v[80:81], v[76:77]
	v_pk_mul_f32 v[66:67], v[70:71], v[66:67]
	v_pk_mul_f32 v[68:69], v[72:73], v[68:69]
	v_pk_mul_f32 v[58:59], v[62:63], v[58:59]
	v_pk_mul_f32 v[60:61], v[64:65], v[60:61]
	v_pk_mul_f32 v[50:51], v[54:55], v[50:51]
	v_pk_mul_f32 v[52:53], v[56:57], v[52:53]
	v_pk_mul_f32 v[42:43], v[46:47], v[42:43]
	v_pk_mul_f32 v[44:45], v[48:49], v[44:45]
	v_pk_mul_f32 v[34:35], v[38:39], v[34:35]
	v_pk_mul_f32 v[36:37], v[40:41], v[36:37]
	v_pk_mul_f32 v[26:27], v[30:31], v[26:27]
	v_pk_mul_f32 v[28:29], v[32:33], v[28:29]
	v_pk_mul_f32 v[18:19], v[22:23], v[18:19]
	v_pk_mul_f32 v[20:21], v[24:25], v[20:21]
	v_pk_mul_f32 v[12:13], v[16:17], v[12:13]
	v_pk_mul_f32 v[10:11], v[14:15], v[10:11]
	v_pk_mul_f32 v[4:5], v[8:9], v[4:5]
	v_pk_mul_f32 v[2:3], v[6:7], v[2:3]
	v_readlane_b32 s97, v252, 18
	v_readlane_b32 s96, v252, 46
	s_waitcnt vmcnt(0)
	v_mov_b32_e32 v146, v145
	v_lshlrev_b64 v[142:143], s42, v[146:147]
	v_min_u32_e32 v142, 1, v142
	s_waitcnt vmcnt(6)
	v_mov_b32_e32 v146, v155
	v_or_b32_e32 v143, v143, v142
	v_cvt_f32_u32_e32 v180, v144
	v_lshlrev_b64 v[144:145], s42, v[146:147]
	v_cvt_f32_u32_e32 v143, v143
	v_min_u32_e32 v146, 1, v144
	v_or_b32_e32 v145, v145, v146
	v_cvt_f32_u32_e32 v154, v154
	v_cvt_f32_u32_e32 v145, v145
	v_fmamk_f32 v142, v180, 0x30000000, v209
	v_ldexp_f32 v143, v143, s93
	v_fmac_f32_e32 v142, 2.0, v143
	v_rsq_f32_e32 v143, v142
	v_fmamk_f32 v144, v154, 0x30000000, v209
	v_ldexp_f32 v145, v145, s93
	v_fmac_f32_e32 v144, 2.0, v145
	v_rsq_f32_e32 v145, v144
	v_mul_f32_e32 v146, 0xbfb8aa3b, v143
	v_pk_mul_f32 v[114:115], v[114:115], v[146:147] op_sel_hi:[1,0]
	v_pk_mul_f32 v[116:117], v[116:117], v[146:147] op_sel_hi:[1,0]
	v_exp_f32_e32 v114, v114
	v_exp_f32_e32 v115, v115
	v_pk_mul_f32 v[110:111], v[110:111], v[146:147] op_sel_hi:[1,0]
	v_pk_mul_f32 v[112:113], v[112:113], v[146:147] op_sel_hi:[1,0]
	v_mul_f32_e32 v146, 0xbfb8aa3b, v145
	v_exp_f32_e32 v116, v116
	v_exp_f32_e32 v117, v117
	v_exp_f32_e32 v110, v110
	v_exp_f32_e32 v111, v111
	v_exp_f32_e32 v112, v112
	v_exp_f32_e32 v113, v113
	v_pk_mul_f32 v[154:155], v[102:103], v[146:147] op_sel_hi:[1,0]
	v_pk_mul_f32 v[106:107], v[106:107], v[146:147] op_sel_hi:[1,0]
	v_exp_f32_e32 v154, v154
	v_exp_f32_e32 v155, v155
	v_pk_mul_f32 v[108:109], v[108:109], v[146:147] op_sel_hi:[1,0]
	v_exp_f32_e32 v106, v106
	v_exp_f32_e32 v107, v107
	v_pk_fma_f32 v[114:115], v[142:143], v[114:115], v[142:143] op_sel_hi:[0,1,0]
	v_pk_mul_f32 v[180:181], v[104:105], v[146:147] op_sel_hi:[1,0]
	v_exp_f32_e32 v108, v108
	v_exp_f32_e32 v109, v109
	v_pk_fma_f32 v[116:117], v[142:143], v[116:117], v[142:143] op_sel_hi:[0,1,0]
	v_rcp_f32_e32 v114, v114
	v_rcp_f32_e32 v115, v115
	v_exp_f32_e32 v180, v180
	v_exp_f32_e32 v181, v181
	v_pk_fma_f32 v[110:111], v[142:143], v[110:111], v[142:143] op_sel_hi:[0,1,0]
	v_pk_fma_f32 v[112:113], v[142:143], v[112:113], v[142:143] op_sel_hi:[0,1,0]
	v_rcp_f32_e32 v116, v116
	v_rcp_f32_e32 v117, v117
	v_rcp_f32_e32 v110, v110
	v_rcp_f32_e32 v111, v111
	v_rcp_f32_e32 v112, v112
	v_rcp_f32_e32 v113, v113
	v_pk_fma_f32 v[142:143], v[144:145], v[154:155], v[144:145] op_sel_hi:[0,1,0]
	v_pk_fma_f32 v[106:107], v[144:145], v[106:107], v[144:145] op_sel_hi:[0,1,0]
	v_rcp_f32_e32 v142, v142
	v_rcp_f32_e32 v143, v143
	v_pk_fma_f32 v[108:109], v[144:145], v[108:109], v[144:145] op_sel_hi:[0,1,0]
	v_rcp_f32_e32 v154, v106
	v_rcp_f32_e32 v155, v107
	v_pk_mul_f32 v[106:107], v[156:157], v[114:115]
	v_pk_fma_f32 v[144:145], v[144:145], v[180:181], v[144:145] op_sel_hi:[0,1,0]
	v_rcp_f32_e32 v180, v108
	v_rcp_f32_e32 v181, v109
	v_pk_mul_f32 v[108:109], v[128:129], v[116:117]
	v_cvt_pk_bf16_f32 v106, v106, v107
	v_pk_mul_f32 v[110:111], v[172:173], v[110:111]
	v_cvt_pk_bf16_f32 v107, v108, v109
	v_pk_mul_f32 v[112:113], v[170:171], v[112:113]
	v_cvt_pk_bf16_f32 v108, v110, v111
	s_waitcnt vmcnt(5)
	v_mov_b32_e32 v146, v179
	v_cvt_pk_bf16_f32 v109, v112, v113
	global_store_dwordx4 v141, v[106:109], s[8:9]
	v_pk_mul_f32 v[102:103], v[98:99], v[142:143]
	v_mov_b32_e32 v99, v146
	v_rcp_f32_e32 v106, v144
	v_rcp_f32_e32 v107, v145
	s_add_u32 s8, s43, s66
	v_pk_mul_f32 v[104:105], v[100:101], v[106:107]
	v_cvt_f32_u32_e32 v100, v178
	v_cvt_f32_u32_e32 v101, v99
	s_addc_u32 s9, s92, s67
	s_add_u32 s8, s8, s88
	v_fmamk_f32 v106, v100, 0x30000000, v209
	v_mov_b32_e32 v100, v101
	v_fmac_f32_e32 v106, 2.0, v100
	v_rsq_f32_e32 v107, v106
	v_pk_mul_f32 v[110:111], v[176:177], v[154:155]
	s_addc_u32 s9, s9, 0
	v_cvt_pk_bf16_f32 v98, v110, v111
	v_pk_mul_f32 v[112:113], v[174:175], v[180:181]
	s_waitcnt vmcnt(5)
	v_mov_b32_e32 v146, v127
	v_cvt_pk_bf16_f32 v99, v112, v113
	v_cvt_pk_bf16_f32 v100, v102, v103
	v_cvt_pk_bf16_f32 v101, v104, v105
	global_store_dwordx4 v141, v[98:101], s[8:9]
	s_add_u32 s8, s43, s70
	s_addc_u32 s9, s92, s71
	v_mul_f32_e32 v98, 0xbfb8aa3b, v107
	v_pk_mul_f32 v[100:101], v[94:95], v[98:99] op_sel_hi:[1,0]
	v_pk_mul_f32 v[94:95], v[86:87], v[98:99] op_sel_hi:[1,0]
	v_pk_mul_f32 v[102:103], v[96:97], v[98:99] op_sel_hi:[1,0]
	v_exp_f32_e32 v94, v94
	v_exp_f32_e32 v95, v95
	v_pk_mul_f32 v[96:97], v[88:89], v[98:99] op_sel_hi:[1,0]
	v_exp_f32_e32 v100, v100
	v_exp_f32_e32 v96, v96
	v_exp_f32_e32 v97, v97
	v_pk_fma_f32 v[94:95], v[106:107], v[94:95], v[106:107] op_sel_hi:[0,1,0]
	v_rcp_f32_e32 v94, v94
	v_rcp_f32_e32 v95, v95
	v_exp_f32_e32 v101, v101
	v_pk_fma_f32 v[96:97], v[106:107], v[96:97], v[106:107] op_sel_hi:[0,1,0]
	v_rcp_f32_e32 v96, v96
	v_rcp_f32_e32 v97, v97
	v_pk_mul_f32 v[86:87], v[82:83], v[94:95]
	v_mov_b32_e32 v83, v146
	v_pk_fma_f32 v[100:101], v[106:107], v[100:101], v[106:107] op_sel_hi:[0,1,0]
	v_rcp_f32_e32 v100, v100
	v_rcp_f32_e32 v101, v101
	v_pk_mul_f32 v[88:89], v[84:85], v[96:97]
	v_cvt_f32_u32_e32 v84, v126
	v_cvt_f32_u32_e32 v85, v83
	v_exp_f32_e32 v102, v102
	v_exp_f32_e32 v103, v103
	v_pk_mul_f32 v[90:91], v[90:91], v[100:101]
	s_add_u32 s8, s8, s88
	v_cvt_pk_bf16_f32 v82, v90, v91
	v_fmamk_f32 v90, v84, 0x30000000, v209
	v_mov_b32_e32 v84, v85
	v_pk_fma_f32 v[102:103], v[106:107], v[102:103], v[106:107] op_sel_hi:[0,1,0]
	v_fmac_f32_e32 v90, 2.0, v84
	v_rcp_f32_e32 v102, v102
	v_rcp_f32_e32 v103, v103
	v_rsq_f32_e32 v91, v90
	s_addc_u32 s9, s9, 0
	s_waitcnt vmcnt(5)
	v_mov_b32_e32 v146, v125
	v_pk_mul_f32 v[92:93], v[92:93], v[102:103]
	s_nop 0
	v_cvt_pk_bf16_f32 v83, v92, v93
	v_cvt_pk_bf16_f32 v84, v86, v87
	v_cvt_pk_bf16_f32 v85, v88, v89
	global_store_dwordx4 v141, v[82:85], s[8:9]
	s_add_u32 s8, s43, s26
	s_addc_u32 s9, s92, s27
	v_mul_f32_e32 v82, 0xbfb8aa3b, v91
	v_pk_mul_f32 v[84:85], v[78:79], v[82:83] op_sel_hi:[1,0]
	v_pk_mul_f32 v[78:79], v[70:71], v[82:83] op_sel_hi:[1,0]
	v_pk_mul_f32 v[86:87], v[80:81], v[82:83] op_sel_hi:[1,0]
	v_exp_f32_e32 v78, v78
	v_exp_f32_e32 v79, v79
	v_pk_mul_f32 v[80:81], v[72:73], v[82:83] op_sel_hi:[1,0]
	v_exp_f32_e32 v84, v84
	v_exp_f32_e32 v80, v80
	v_exp_f32_e32 v81, v81
	v_pk_fma_f32 v[78:79], v[90:91], v[78:79], v[90:91] op_sel_hi:[0,1,0]
	v_rcp_f32_e32 v78, v78
	v_rcp_f32_e32 v79, v79
	v_exp_f32_e32 v85, v85
	v_pk_fma_f32 v[80:81], v[90:91], v[80:81], v[90:91] op_sel_hi:[0,1,0]
	v_rcp_f32_e32 v80, v80
	v_rcp_f32_e32 v81, v81
	v_pk_mul_f32 v[70:71], v[66:67], v[78:79]
	v_mov_b32_e32 v67, v146
	v_pk_fma_f32 v[84:85], v[90:91], v[84:85], v[90:91] op_sel_hi:[0,1,0]
	v_rcp_f32_e32 v84, v84
	v_rcp_f32_e32 v85, v85
	v_pk_mul_f32 v[72:73], v[68:69], v[80:81]
	v_cvt_f32_u32_e32 v68, v124
	v_cvt_f32_u32_e32 v69, v67
	v_exp_f32_e32 v86, v86
	v_exp_f32_e32 v87, v87
	v_pk_mul_f32 v[74:75], v[74:75], v[84:85]
	s_add_u32 s8, s8, s88
	v_cvt_pk_bf16_f32 v66, v74, v75
	v_fmamk_f32 v74, v68, 0x30000000, v209
	v_mov_b32_e32 v68, v69
	v_pk_fma_f32 v[86:87], v[90:91], v[86:87], v[90:91] op_sel_hi:[0,1,0]
	v_fmac_f32_e32 v74, 2.0, v68
	v_rcp_f32_e32 v86, v86
	v_rcp_f32_e32 v87, v87
	v_rsq_f32_e32 v75, v74
	s_addc_u32 s9, s9, 0
	s_waitcnt vmcnt(5)
	v_mov_b32_e32 v146, v123
	v_pk_mul_f32 v[76:77], v[76:77], v[86:87]
	s_nop 0
	v_cvt_pk_bf16_f32 v67, v76, v77
	v_cvt_pk_bf16_f32 v68, v70, v71
	v_cvt_pk_bf16_f32 v69, v72, v73
	global_store_dwordx4 v141, v[66:69], s[8:9]
	s_add_u32 s8, s43, s22
	s_addc_u32 s9, s92, s82
	v_mul_f32_e32 v66, 0xbfb8aa3b, v75
	v_pk_mul_f32 v[68:69], v[62:63], v[66:67] op_sel_hi:[1,0]
	v_pk_mul_f32 v[62:63], v[54:55], v[66:67] op_sel_hi:[1,0]
	v_pk_mul_f32 v[70:71], v[64:65], v[66:67] op_sel_hi:[1,0]
	v_exp_f32_e32 v62, v62
	v_exp_f32_e32 v63, v63
	v_pk_mul_f32 v[64:65], v[56:57], v[66:67] op_sel_hi:[1,0]
	v_exp_f32_e32 v68, v68
	v_exp_f32_e32 v64, v64
	v_exp_f32_e32 v65, v65
	v_pk_fma_f32 v[62:63], v[74:75], v[62:63], v[74:75] op_sel_hi:[0,1,0]
	v_rcp_f32_e32 v62, v62
	v_rcp_f32_e32 v63, v63
	v_exp_f32_e32 v69, v69
	v_pk_fma_f32 v[64:65], v[74:75], v[64:65], v[74:75] op_sel_hi:[0,1,0]
	v_rcp_f32_e32 v64, v64
	v_rcp_f32_e32 v65, v65
	v_pk_mul_f32 v[54:55], v[50:51], v[62:63]
	v_mov_b32_e32 v51, v146
	v_pk_fma_f32 v[68:69], v[74:75], v[68:69], v[74:75] op_sel_hi:[0,1,0]
	v_rcp_f32_e32 v68, v68
	v_rcp_f32_e32 v69, v69
	v_pk_mul_f32 v[56:57], v[52:53], v[64:65]
	v_cvt_f32_u32_e32 v52, v122
	v_cvt_f32_u32_e32 v53, v51
	v_exp_f32_e32 v70, v70
	v_exp_f32_e32 v71, v71
	v_pk_mul_f32 v[58:59], v[58:59], v[68:69]
	s_add_u32 s8, s8, s88
	v_cvt_pk_bf16_f32 v50, v58, v59
	v_fmamk_f32 v58, v52, 0x30000000, v209
	v_mov_b32_e32 v52, v53
	v_pk_fma_f32 v[70:71], v[74:75], v[70:71], v[74:75] op_sel_hi:[0,1,0]
	v_fmac_f32_e32 v58, 2.0, v52
	v_rcp_f32_e32 v70, v70
	v_rcp_f32_e32 v71, v71
	v_rsq_f32_e32 v59, v58
	s_addc_u32 s9, s9, 0
	s_waitcnt vmcnt(5)
	v_mov_b32_e32 v146, v121
	v_pk_mul_f32 v[60:61], v[60:61], v[70:71]
	s_nop 0
	v_cvt_pk_bf16_f32 v51, v60, v61
	v_cvt_pk_bf16_f32 v52, v54, v55
	v_cvt_pk_bf16_f32 v53, v56, v57
	global_store_dwordx4 v141, v[50:53], s[8:9]
	s_add_u32 s8, s43, s12
	s_addc_u32 s9, s92, s83
	v_mul_f32_e32 v50, 0xbfb8aa3b, v59
	v_pk_mul_f32 v[52:53], v[46:47], v[50:51] op_sel_hi:[1,0]
	v_pk_mul_f32 v[46:47], v[38:39], v[50:51] op_sel_hi:[1,0]
	v_pk_mul_f32 v[54:55], v[48:49], v[50:51] op_sel_hi:[1,0]
	v_exp_f32_e32 v46, v46
	v_exp_f32_e32 v47, v47
	v_pk_mul_f32 v[48:49], v[40:41], v[50:51] op_sel_hi:[1,0]
	v_exp_f32_e32 v52, v52
	v_exp_f32_e32 v48, v48
	v_exp_f32_e32 v49, v49
	v_pk_fma_f32 v[46:47], v[58:59], v[46:47], v[58:59] op_sel_hi:[0,1,0]
	v_rcp_f32_e32 v46, v46
	v_rcp_f32_e32 v47, v47
	v_exp_f32_e32 v53, v53
	v_pk_fma_f32 v[48:49], v[58:59], v[48:49], v[58:59] op_sel_hi:[0,1,0]
	v_rcp_f32_e32 v48, v48
	v_rcp_f32_e32 v49, v49
	v_pk_mul_f32 v[38:39], v[34:35], v[46:47]
	v_mov_b32_e32 v35, v146
	v_pk_fma_f32 v[52:53], v[58:59], v[52:53], v[58:59] op_sel_hi:[0,1,0]
	v_rcp_f32_e32 v52, v52
	v_rcp_f32_e32 v53, v53
	v_pk_mul_f32 v[40:41], v[36:37], v[48:49]
	v_cvt_f32_u32_e32 v36, v120
	v_cvt_f32_u32_e32 v37, v35
	v_exp_f32_e32 v54, v54
	v_exp_f32_e32 v55, v55
	v_pk_mul_f32 v[42:43], v[42:43], v[52:53]
	s_add_u32 s8, s8, s88
	v_cvt_pk_bf16_f32 v34, v42, v43
	v_fmamk_f32 v42, v36, 0x30000000, v209
	v_mov_b32_e32 v36, v37
	v_pk_fma_f32 v[54:55], v[58:59], v[54:55], v[58:59] op_sel_hi:[0,1,0]
	v_fmac_f32_e32 v42, 2.0, v36
	v_rcp_f32_e32 v54, v54
	v_rcp_f32_e32 v55, v55
	v_rsq_f32_e32 v43, v42
	s_addc_u32 s9, s9, 0
	s_waitcnt vmcnt(5)
	v_mov_b32_e32 v146, v119
	v_pk_mul_f32 v[44:45], v[44:45], v[54:55]
	s_nop 0
	v_cvt_pk_bf16_f32 v35, v44, v45
	v_cvt_pk_bf16_f32 v36, v38, v39
	v_cvt_pk_bf16_f32 v37, v40, v41
	global_store_dwordx4 v141, v[34:37], s[8:9]
	s_add_u32 s8, s43, s84
	s_addc_u32 s9, s92, s85
	v_mul_f32_e32 v34, 0xbfb8aa3b, v43
	v_pk_mul_f32 v[36:37], v[30:31], v[34:35] op_sel_hi:[1,0]
	v_pk_mul_f32 v[30:31], v[22:23], v[34:35] op_sel_hi:[1,0]
	v_pk_mul_f32 v[38:39], v[32:33], v[34:35] op_sel_hi:[1,0]
	v_exp_f32_e32 v30, v30
	v_exp_f32_e32 v31, v31
	v_pk_mul_f32 v[32:33], v[24:25], v[34:35] op_sel_hi:[1,0]
	v_exp_f32_e32 v36, v36
	v_exp_f32_e32 v32, v32
	v_exp_f32_e32 v33, v33
	v_pk_fma_f32 v[30:31], v[42:43], v[30:31], v[42:43] op_sel_hi:[0,1,0]
	v_rcp_f32_e32 v30, v30
	v_rcp_f32_e32 v31, v31
	v_exp_f32_e32 v37, v37
	v_pk_fma_f32 v[32:33], v[42:43], v[32:33], v[42:43] op_sel_hi:[0,1,0]
	v_rcp_f32_e32 v32, v32
	v_rcp_f32_e32 v33, v33
	v_pk_mul_f32 v[22:23], v[18:19], v[30:31]
	v_mov_b32_e32 v19, v146
	v_pk_fma_f32 v[36:37], v[42:43], v[36:37], v[42:43] op_sel_hi:[0,1,0]
	v_rcp_f32_e32 v36, v36
	v_rcp_f32_e32 v37, v37
	v_pk_mul_f32 v[24:25], v[20:21], v[32:33]
	v_cvt_f32_u32_e32 v20, v118
	v_cvt_f32_u32_e32 v21, v19
	v_exp_f32_e32 v38, v38
	v_exp_f32_e32 v39, v39
	v_pk_mul_f32 v[26:27], v[26:27], v[36:37]
	s_add_u32 s8, s8, s88
	v_cvt_pk_bf16_f32 v18, v26, v27
	v_fmamk_f32 v26, v20, 0x30000000, v209
	v_mov_b32_e32 v20, v21
	v_pk_fma_f32 v[38:39], v[42:43], v[38:39], v[42:43] op_sel_hi:[0,1,0]
	v_fmac_f32_e32 v26, 2.0, v20
	v_rcp_f32_e32 v38, v38
	v_rcp_f32_e32 v39, v39
	v_rsq_f32_e32 v27, v26
	s_addc_u32 s9, s9, 0
	v_pk_mul_f32 v[28:29], v[28:29], v[38:39]
	s_nop 0
	v_cvt_pk_bf16_f32 v19, v28, v29
	v_cvt_pk_bf16_f32 v20, v22, v23
	v_cvt_pk_bf16_f32 v21, v24, v25
	global_store_dwordx4 v141, v[18:21], s[8:9]
	s_add_u32 s8, s43, s86
	s_addc_u32 s9, s92, s87
	v_mul_f32_e32 v18, 0xbfb8aa3b, v27
	v_pk_mul_f32 v[20:21], v[14:15], v[18:19] op_sel_hi:[1,0]
	v_pk_mul_f32 v[22:23], v[16:17], v[18:19] op_sel_hi:[1,0]
	v_pk_mul_f32 v[14:15], v[6:7], v[18:19] op_sel_hi:[1,0]
	v_pk_mul_f32 v[16:17], v[8:9], v[18:19] op_sel_hi:[1,0]
	v_exp_f32_e32 v20, v20
	v_exp_f32_e32 v21, v21
	v_exp_f32_e32 v22, v22
	v_exp_f32_e32 v23, v23
	v_exp_f32_e32 v14, v14
	v_exp_f32_e32 v15, v15
	v_exp_f32_e32 v16, v16
	v_exp_f32_e32 v17, v17
	v_pk_fma_f32 v[20:21], v[26:27], v[20:21], v[26:27] op_sel_hi:[0,1,0]
	v_pk_fma_f32 v[22:23], v[26:27], v[22:23], v[26:27] op_sel_hi:[0,1,0]
	v_pk_fma_f32 v[14:15], v[26:27], v[14:15], v[26:27] op_sel_hi:[0,1,0]
	v_pk_fma_f32 v[16:17], v[26:27], v[16:17], v[26:27] op_sel_hi:[0,1,0]
	v_rcp_f32_e32 v20, v20
	v_rcp_f32_e32 v21, v21
	v_rcp_f32_e32 v22, v22
	v_rcp_f32_e32 v23, v23
	v_rcp_f32_e32 v14, v14
	v_rcp_f32_e32 v15, v15
	v_rcp_f32_e32 v16, v16
	v_rcp_f32_e32 v17, v17
	s_add_u32 s8, s8, s88
	s_addc_u32 s9, s9, 0
	v_pk_mul_f32 v[10:11], v[10:11], v[20:21]
	v_pk_mul_f32 v[12:13], v[12:13], v[22:23]
	v_pk_mul_f32 v[6:7], v[2:3], v[14:15]
	v_pk_mul_f32 v[8:9], v[4:5], v[16:17]
	v_cvt_pk_bf16_f32 v2, v10, v11
	v_cvt_pk_bf16_f32 v3, v12, v13
	v_cvt_pk_bf16_f32 v4, v6, v7
	s_andn2_b64 vcc, exec, s[34:35]
	v_cvt_pk_bf16_f32 v5, v8, v9
	global_store_dwordx4 v141, v[2:5], s[8:9]
	s_mov_b64 s[8:9], -1
	s_cbranch_vccnz .LBB0_293
	s_andn2_b64 vcc, exec, s[44:45]
	s_cbranch_vccnz .LBB0_292
	s_barrier
	s_branch .LBB0_292

.LBB0_1883:
	s_lshl_b32 s8, s93, 8
	s_add_i32 s8, s8, s46
	s_ashr_i32 s9, s8, 31
	v_lshl_add_u64 v[140:141], s[8:9], 3, v[130:131]
	global_load_dwordx2 v[142:143], v[140:141], off
	global_load_dwordx2 v[144:145], v[140:141], off offset:128
	v_pk_mul_f32 v[154:155], v[114:115], v[126:127]
	v_pk_mul_f32 v[156:157], v[112:113], v[124:125]
	v_pk_mul_f32 v[170:171], v[110:111], v[122:123]
	v_pk_mul_f32 v[172:173], v[108:109], v[120:121]
	v_pk_mul_f32 v[174:175], v[106:107], v[118:119]
	global_load_dwordx2 v[176:177], v[140:141], off offset:256
	global_load_dwordx2 v[126:127], v[140:141], off offset:384
	global_load_dwordx2 v[124:125], v[140:141], off offset:1024
	global_load_dwordx2 v[122:123], v[140:141], off offset:1152
	global_load_dwordx2 v[120:121], v[140:141], off offset:1280
	global_load_dwordx2 v[118:119], v[140:141], off offset:1408
	s_flbit_i32_b32 s8, 0
	s_min_u32 s42, s8, 32
	s_mul_i32 s8, s93, 0x58
	s_sub_i32 s93, 32, s42
	v_pk_mul_f32 v[128:129], v[116:117], v[128:129]
	s_lshl_b32 s9, s90, 1
	s_or_b32 s9, s9, s73
	s_add_i32 s8, s9, s8
	s_ashr_i32 s9, s8, 31
	s_lshl_b64 s[8:9], s[8:9], 15
	s_add_u32 s43, s25, s8
	s_addc_u32 s90, s30, s9
	s_add_u32 s8, s43, s66
	s_addc_u32 s9, s90, s67
	s_add_u32 s8, s8, s88
	s_addc_u32 s9, s9, 0
	v_pk_mul_f32 v[98:99], v[102:103], v[98:99]
	v_pk_mul_f32 v[100:101], v[104:105], v[100:101]
	v_pk_mul_f32 v[90:91], v[94:95], v[90:91]
	v_pk_mul_f32 v[92:93], v[96:97], v[92:93]
	v_pk_mul_f32 v[82:83], v[86:87], v[82:83]
	v_pk_mul_f32 v[84:85], v[88:89], v[84:85]
	v_pk_mul_f32 v[74:75], v[78:79], v[74:75]
	v_pk_mul_f32 v[76:77], v[80:81], v[76:77]
	v_pk_mul_f32 v[66:67], v[70:71], v[66:67]
	v_pk_mul_f32 v[68:69], v[72:73], v[68:69]
	v_pk_mul_f32 v[58:59], v[62:63], v[58:59]
	v_pk_mul_f32 v[60:61], v[64:65], v[60:61]
	v_pk_mul_f32 v[50:51], v[54:55], v[50:51]
	v_pk_mul_f32 v[52:53], v[56:57], v[52:53]
	v_pk_mul_f32 v[42:43], v[46:47], v[42:43]
	v_pk_mul_f32 v[44:45], v[48:49], v[44:45]
	v_pk_mul_f32 v[34:35], v[38:39], v[34:35]
	v_pk_mul_f32 v[36:37], v[40:41], v[36:37]
	v_pk_mul_f32 v[26:27], v[30:31], v[26:27]
	v_pk_mul_f32 v[28:29], v[32:33], v[28:29]
	v_pk_mul_f32 v[18:19], v[22:23], v[18:19]
	v_pk_mul_f32 v[20:21], v[24:25], v[20:21]
	v_pk_mul_f32 v[12:13], v[16:17], v[12:13]
	v_pk_mul_f32 v[10:11], v[14:15], v[10:11]
	v_pk_mul_f32 v[4:5], v[8:9], v[4:5]
	v_pk_mul_f32 v[2:3], v[6:7], v[2:3]
	v_readlane_b32 s96, v252, 46
	s_waitcnt vmcnt(0)
	v_cvt_f32_u32_e32 v139, v142
	v_mov_b32_e32 v146, v143
	v_mov_b32_e32 v141, v146
	v_mov_b32_e32 v146, v145
	v_lshlrev_b64 v[142:143], s42, v[146:147]
	v_fmamk_f32 v140, v139, 0x30000000, v209
	v_cvt_f32_u32_e32 v139, v141
	v_min_u32_e32 v145, 1, v142
	v_or_b32_e32 v141, v143, v145
	v_cvt_f32_u32_e32 v144, v144
	v_cvt_f32_u32_e32 v141, v141
	v_fmac_f32_e32 v140, 2.0, v139
	v_rsq_f32_e32 v139, v140
	v_fmamk_f32 v142, v144, 0x30000000, v209
	v_ldexp_f32 v141, v141, s93
	v_fmac_f32_e32 v142, 2.0, v141
	v_rsq_f32_e32 v141, v142
	v_mul_f32_e32 v144, 0xbfb8aa3b, v139
	v_pk_mul_f32 v[114:115], v[114:115], v[144:145] op_sel_hi:[1,0]
	v_pk_mul_f32 v[116:117], v[116:117], v[144:145] op_sel_hi:[1,0]
	v_exp_f32_e32 v114, v114
	v_exp_f32_e32 v115, v115
	v_pk_mul_f32 v[110:111], v[110:111], v[144:145] op_sel_hi:[1,0]
	v_pk_mul_f32 v[112:113], v[112:113], v[144:145] op_sel_hi:[1,0]
	v_mul_f32_e32 v144, 0xbfb8aa3b, v141
	v_exp_f32_e32 v116, v116
	v_exp_f32_e32 v117, v117
	v_exp_f32_e32 v110, v110
	v_exp_f32_e32 v111, v111
	v_exp_f32_e32 v112, v112
	v_exp_f32_e32 v113, v113
	v_pk_mul_f32 v[178:179], v[102:103], v[144:145] op_sel_hi:[1,0]
	v_pk_mul_f32 v[106:107], v[106:107], v[144:145] op_sel_hi:[1,0]
	v_exp_f32_e32 v178, v178
	v_exp_f32_e32 v179, v179
	v_pk_mul_f32 v[108:109], v[108:109], v[144:145] op_sel_hi:[1,0]
	v_pk_mul_f32 v[144:145], v[104:105], v[144:145] op_sel_hi:[1,0]
	v_exp_f32_e32 v106, v106
	v_exp_f32_e32 v107, v107
	v_pk_fma_f32 v[114:115], v[140:141], v[114:115], v[140:141] op_sel_hi:[0,1,0]
	v_exp_f32_e32 v108, v108
	v_exp_f32_e32 v109, v109
	v_exp_f32_e32 v144, v144
	v_exp_f32_e32 v145, v145
	v_pk_fma_f32 v[116:117], v[140:141], v[116:117], v[140:141] op_sel_hi:[0,1,0]
	v_rcp_f32_e32 v114, v114
	v_rcp_f32_e32 v115, v115
	v_pk_fma_f32 v[110:111], v[140:141], v[110:111], v[140:141] op_sel_hi:[0,1,0]
	v_pk_fma_f32 v[112:113], v[140:141], v[112:113], v[140:141] op_sel_hi:[0,1,0]
	v_rcp_f32_e32 v116, v116
	v_rcp_f32_e32 v117, v117
	v_rcp_f32_e32 v110, v110
	v_rcp_f32_e32 v111, v111
	v_rcp_f32_e32 v112, v112
	v_rcp_f32_e32 v113, v113
	v_pk_fma_f32 v[140:141], v[142:143], v[178:179], v[142:143] op_sel_hi:[0,1,0]
	v_pk_fma_f32 v[106:107], v[142:143], v[106:107], v[142:143] op_sel_hi:[0,1,0]
	v_rcp_f32_e32 v140, v140
	v_rcp_f32_e32 v141, v141
	v_pk_fma_f32 v[108:109], v[142:143], v[108:109], v[142:143] op_sel_hi:[0,1,0]
	v_pk_fma_f32 v[142:143], v[142:143], v[144:145], v[142:143] op_sel_hi:[0,1,0]
	v_rcp_f32_e32 v144, v106
	v_rcp_f32_e32 v145, v107
	v_pk_mul_f32 v[106:107], v[154:155], v[114:115]
	v_rcp_f32_e32 v178, v108
	v_rcp_f32_e32 v179, v109
	v_pk_mul_f32 v[108:109], v[128:129], v[116:117]
	v_cvt_pk_bf16_f32 v106, v106, v107
	v_pk_mul_f32 v[110:111], v[170:171], v[110:111]
	v_cvt_pk_bf16_f32 v107, v108, v109
	v_pk_mul_f32 v[112:113], v[156:157], v[112:113]
	v_cvt_pk_bf16_f32 v108, v110, v111
	v_mov_b32_e32 v146, v177
	v_cvt_pk_bf16_f32 v109, v112, v113
	global_store_dwordx4 v138, v[106:109], s[8:9]
	v_pk_mul_f32 v[102:103], v[98:99], v[140:141]
	v_mov_b32_e32 v99, v146
	v_rcp_f32_e32 v106, v142
	v_rcp_f32_e32 v107, v143
	s_add_u32 s8, s43, s68
	v_pk_mul_f32 v[104:105], v[100:101], v[106:107]
	v_cvt_f32_u32_e32 v100, v176
	v_cvt_f32_u32_e32 v101, v99
	s_addc_u32 s9, s90, s69
	s_add_u32 s8, s8, s88
	v_fmamk_f32 v106, v100, 0x30000000, v209
	v_mov_b32_e32 v100, v101
	v_fmac_f32_e32 v106, 2.0, v100
	v_rsq_f32_e32 v107, v106
	v_pk_mul_f32 v[110:111], v[174:175], v[144:145]
	s_addc_u32 s9, s9, 0
	v_cvt_pk_bf16_f32 v98, v110, v111
	v_pk_mul_f32 v[112:113], v[172:173], v[178:179]
	v_mov_b32_e32 v146, v127
	v_cvt_pk_bf16_f32 v99, v112, v113
	v_cvt_pk_bf16_f32 v100, v102, v103
	v_cvt_pk_bf16_f32 v101, v104, v105
	global_store_dwordx4 v138, v[98:101], s[8:9]
	s_add_u32 s8, s43, s70
	s_addc_u32 s9, s90, s71
	v_mul_f32_e32 v98, 0xbfb8aa3b, v107
	v_pk_mul_f32 v[100:101], v[94:95], v[98:99] op_sel_hi:[1,0]
	v_pk_mul_f32 v[94:95], v[86:87], v[98:99] op_sel_hi:[1,0]
	v_pk_mul_f32 v[102:103], v[96:97], v[98:99] op_sel_hi:[1,0]
	v_exp_f32_e32 v94, v94
	v_exp_f32_e32 v95, v95
	v_pk_mul_f32 v[96:97], v[88:89], v[98:99] op_sel_hi:[1,0]
	v_exp_f32_e32 v100, v100
	v_exp_f32_e32 v96, v96
	v_exp_f32_e32 v97, v97
	v_pk_fma_f32 v[94:95], v[106:107], v[94:95], v[106:107] op_sel_hi:[0,1,0]
	v_rcp_f32_e32 v94, v94
	v_rcp_f32_e32 v95, v95
	v_exp_f32_e32 v101, v101
	v_pk_fma_f32 v[96:97], v[106:107], v[96:97], v[106:107] op_sel_hi:[0,1,0]
	v_rcp_f32_e32 v96, v96
	v_rcp_f32_e32 v97, v97
	v_pk_mul_f32 v[86:87], v[82:83], v[94:95]
	v_mov_b32_e32 v83, v146
	v_pk_fma_f32 v[100:101], v[106:107], v[100:101], v[106:107] op_sel_hi:[0,1,0]
	v_rcp_f32_e32 v100, v100
	v_rcp_f32_e32 v101, v101
	v_pk_mul_f32 v[88:89], v[84:85], v[96:97]
	v_cvt_f32_u32_e32 v84, v126
	v_cvt_f32_u32_e32 v85, v83
	v_exp_f32_e32 v102, v102
	v_exp_f32_e32 v103, v103
	v_pk_mul_f32 v[90:91], v[90:91], v[100:101]
	s_add_u32 s8, s8, s88
	v_cvt_pk_bf16_f32 v82, v90, v91
	v_fmamk_f32 v90, v84, 0x30000000, v209
	v_mov_b32_e32 v84, v85
	v_pk_fma_f32 v[102:103], v[106:107], v[102:103], v[106:107] op_sel_hi:[0,1,0]
	v_fmac_f32_e32 v90, 2.0, v84
	v_rcp_f32_e32 v102, v102
	v_rcp_f32_e32 v103, v103
	v_rsq_f32_e32 v91, v90
	s_addc_u32 s9, s9, 0
	v_mov_b32_e32 v146, v125
	v_pk_mul_f32 v[92:93], v[92:93], v[102:103]
	s_nop 0
	v_cvt_pk_bf16_f32 v83, v92, v93
	v_cvt_pk_bf16_f32 v84, v86, v87
	v_cvt_pk_bf16_f32 v85, v88, v89
	global_store_dwordx4 v138, v[82:85], s[8:9]
	s_add_u32 s8, s43, s26
	s_addc_u32 s9, s90, s27
	v_mul_f32_e32 v82, 0xbfb8aa3b, v91
	v_pk_mul_f32 v[84:85], v[78:79], v[82:83] op_sel_hi:[1,0]
	v_pk_mul_f32 v[78:79], v[70:71], v[82:83] op_sel_hi:[1,0]
	v_pk_mul_f32 v[86:87], v[80:81], v[82:83] op_sel_hi:[1,0]
	v_exp_f32_e32 v78, v78
	v_exp_f32_e32 v79, v79
	v_pk_mul_f32 v[80:81], v[72:73], v[82:83] op_sel_hi:[1,0]
	v_exp_f32_e32 v84, v84
	v_exp_f32_e32 v80, v80
	v_exp_f32_e32 v81, v81
	v_pk_fma_f32 v[78:79], v[90:91], v[78:79], v[90:91] op_sel_hi:[0,1,0]
	v_rcp_f32_e32 v78, v78
	v_rcp_f32_e32 v79, v79
	v_exp_f32_e32 v85, v85
	v_pk_fma_f32 v[80:81], v[90:91], v[80:81], v[90:91] op_sel_hi:[0,1,0]
	v_rcp_f32_e32 v80, v80
	v_rcp_f32_e32 v81, v81
	v_pk_mul_f32 v[70:71], v[66:67], v[78:79]
	v_mov_b32_e32 v67, v146
	v_pk_fma_f32 v[84:85], v[90:91], v[84:85], v[90:91] op_sel_hi:[0,1,0]
	v_rcp_f32_e32 v84, v84
	v_rcp_f32_e32 v85, v85
	v_pk_mul_f32 v[72:73], v[68:69], v[80:81]
	v_cvt_f32_u32_e32 v68, v124
	v_cvt_f32_u32_e32 v69, v67
	v_exp_f32_e32 v86, v86
	v_exp_f32_e32 v87, v87
	v_pk_mul_f32 v[74:75], v[74:75], v[84:85]
	s_add_u32 s8, s8, s88
	v_cvt_pk_bf16_f32 v66, v74, v75
	v_fmamk_f32 v74, v68, 0x30000000, v209
	v_mov_b32_e32 v68, v69
	v_pk_fma_f32 v[86:87], v[90:91], v[86:87], v[90:91] op_sel_hi:[0,1,0]
	v_fmac_f32_e32 v74, 2.0, v68
	v_rcp_f32_e32 v86, v86
	v_rcp_f32_e32 v87, v87
	v_rsq_f32_e32 v75, v74
	s_addc_u32 s9, s9, 0
	v_mov_b32_e32 v146, v123
	v_pk_mul_f32 v[76:77], v[76:77], v[86:87]
	s_nop 0
	v_cvt_pk_bf16_f32 v67, v76, v77
	v_cvt_pk_bf16_f32 v68, v70, v71
	v_cvt_pk_bf16_f32 v69, v72, v73
	global_store_dwordx4 v138, v[66:69], s[8:9]
	s_add_u32 s8, s43, s82
	s_addc_u32 s9, s90, s84
	v_mul_f32_e32 v66, 0xbfb8aa3b, v75
	v_pk_mul_f32 v[68:69], v[62:63], v[66:67] op_sel_hi:[1,0]
	v_pk_mul_f32 v[62:63], v[54:55], v[66:67] op_sel_hi:[1,0]
	v_pk_mul_f32 v[70:71], v[64:65], v[66:67] op_sel_hi:[1,0]
	v_exp_f32_e32 v62, v62
	v_exp_f32_e32 v63, v63
	v_pk_mul_f32 v[64:65], v[56:57], v[66:67] op_sel_hi:[1,0]
	v_exp_f32_e32 v68, v68
	v_exp_f32_e32 v64, v64
	v_exp_f32_e32 v65, v65
	v_pk_fma_f32 v[62:63], v[74:75], v[62:63], v[74:75] op_sel_hi:[0,1,0]
	v_rcp_f32_e32 v62, v62
	v_rcp_f32_e32 v63, v63
	v_exp_f32_e32 v69, v69
	v_pk_fma_f32 v[64:65], v[74:75], v[64:65], v[74:75] op_sel_hi:[0,1,0]
	v_rcp_f32_e32 v64, v64
	v_rcp_f32_e32 v65, v65
	v_pk_mul_f32 v[54:55], v[50:51], v[62:63]
	v_mov_b32_e32 v51, v146
	v_pk_fma_f32 v[68:69], v[74:75], v[68:69], v[74:75] op_sel_hi:[0,1,0]
	v_rcp_f32_e32 v68, v68
	v_rcp_f32_e32 v69, v69
	v_pk_mul_f32 v[56:57], v[52:53], v[64:65]
	v_cvt_f32_u32_e32 v52, v122
	v_cvt_f32_u32_e32 v53, v51
	v_exp_f32_e32 v70, v70
	v_exp_f32_e32 v71, v71
	v_pk_mul_f32 v[58:59], v[58:59], v[68:69]
	s_add_u32 s8, s8, s88
	v_cvt_pk_bf16_f32 v50, v58, v59
	v_fmamk_f32 v58, v52, 0x30000000, v209
	v_mov_b32_e32 v52, v53
	v_pk_fma_f32 v[70:71], v[74:75], v[70:71], v[74:75] op_sel_hi:[0,1,0]
	v_fmac_f32_e32 v58, 2.0, v52
	v_rcp_f32_e32 v70, v70
	v_rcp_f32_e32 v71, v71
	v_rsq_f32_e32 v59, v58
	s_addc_u32 s9, s9, 0
	v_mov_b32_e32 v146, v121
	v_pk_mul_f32 v[60:61], v[60:61], v[70:71]
	s_nop 0
	v_cvt_pk_bf16_f32 v51, v60, v61
	v_cvt_pk_bf16_f32 v52, v54, v55
	v_cvt_pk_bf16_f32 v53, v56, v57
	global_store_dwordx4 v138, v[50:53], s[8:9]
	s_add_u32 s8, s43, s85
	s_addc_u32 s9, s90, s22
	v_mul_f32_e32 v50, 0xbfb8aa3b, v59
	v_pk_mul_f32 v[52:53], v[46:47], v[50:51] op_sel_hi:[1,0]
	v_pk_mul_f32 v[46:47], v[38:39], v[50:51] op_sel_hi:[1,0]
	v_pk_mul_f32 v[54:55], v[48:49], v[50:51] op_sel_hi:[1,0]
	v_exp_f32_e32 v46, v46
	v_exp_f32_e32 v47, v47
	v_pk_mul_f32 v[48:49], v[40:41], v[50:51] op_sel_hi:[1,0]
	v_exp_f32_e32 v52, v52
	v_exp_f32_e32 v48, v48
	v_exp_f32_e32 v49, v49
	v_pk_fma_f32 v[46:47], v[58:59], v[46:47], v[58:59] op_sel_hi:[0,1,0]
	v_rcp_f32_e32 v46, v46
	v_rcp_f32_e32 v47, v47
	v_exp_f32_e32 v53, v53
	v_pk_fma_f32 v[48:49], v[58:59], v[48:49], v[58:59] op_sel_hi:[0,1,0]
	v_rcp_f32_e32 v48, v48
	v_rcp_f32_e32 v49, v49
	v_pk_mul_f32 v[38:39], v[34:35], v[46:47]
	v_mov_b32_e32 v35, v146
	v_pk_fma_f32 v[52:53], v[58:59], v[52:53], v[58:59] op_sel_hi:[0,1,0]
	v_rcp_f32_e32 v52, v52
	v_rcp_f32_e32 v53, v53
	v_pk_mul_f32 v[40:41], v[36:37], v[48:49]
	v_cvt_f32_u32_e32 v36, v120
	v_cvt_f32_u32_e32 v37, v35
	v_exp_f32_e32 v54, v54
	v_exp_f32_e32 v55, v55
	v_pk_mul_f32 v[42:43], v[42:43], v[52:53]
	s_add_u32 s8, s8, s88
	v_cvt_pk_bf16_f32 v34, v42, v43
	v_fmamk_f32 v42, v36, 0x30000000, v209
	v_mov_b32_e32 v36, v37
	v_pk_fma_f32 v[54:55], v[58:59], v[54:55], v[58:59] op_sel_hi:[0,1,0]
	v_fmac_f32_e32 v42, 2.0, v36
	v_rcp_f32_e32 v54, v54
	v_rcp_f32_e32 v55, v55
	v_rsq_f32_e32 v43, v42
	s_addc_u32 s9, s9, 0
	v_mov_b32_e32 v146, v119
	v_pk_mul_f32 v[44:45], v[44:45], v[54:55]
	s_nop 0
	v_cvt_pk_bf16_f32 v35, v44, v45
	v_cvt_pk_bf16_f32 v36, v38, v39
	v_cvt_pk_bf16_f32 v37, v40, v41
	global_store_dwordx4 v138, v[34:37], s[8:9]
	s_add_u32 s8, s43, s83
	s_addc_u32 s9, s90, s12
	v_mul_f32_e32 v34, 0xbfb8aa3b, v43
	v_pk_mul_f32 v[36:37], v[30:31], v[34:35] op_sel_hi:[1,0]
	v_pk_mul_f32 v[30:31], v[22:23], v[34:35] op_sel_hi:[1,0]
	v_pk_mul_f32 v[38:39], v[32:33], v[34:35] op_sel_hi:[1,0]
	v_exp_f32_e32 v30, v30
	v_exp_f32_e32 v31, v31
	v_pk_mul_f32 v[32:33], v[24:25], v[34:35] op_sel_hi:[1,0]
	v_exp_f32_e32 v36, v36
	v_exp_f32_e32 v32, v32
	v_exp_f32_e32 v33, v33
	v_pk_fma_f32 v[30:31], v[42:43], v[30:31], v[42:43] op_sel_hi:[0,1,0]
	v_rcp_f32_e32 v30, v30
	v_rcp_f32_e32 v31, v31
	v_exp_f32_e32 v37, v37
	v_pk_fma_f32 v[32:33], v[42:43], v[32:33], v[42:43] op_sel_hi:[0,1,0]
	v_rcp_f32_e32 v32, v32
	v_rcp_f32_e32 v33, v33
	v_pk_mul_f32 v[22:23], v[18:19], v[30:31]
	v_mov_b32_e32 v19, v146
	v_pk_fma_f32 v[36:37], v[42:43], v[36:37], v[42:43] op_sel_hi:[0,1,0]
	v_rcp_f32_e32 v36, v36
	v_rcp_f32_e32 v37, v37
	v_pk_mul_f32 v[24:25], v[20:21], v[32:33]
	v_cvt_f32_u32_e32 v20, v118
	v_cvt_f32_u32_e32 v21, v19
	v_exp_f32_e32 v38, v38
	v_exp_f32_e32 v39, v39
	v_pk_mul_f32 v[26:27], v[26:27], v[36:37]
	s_add_u32 s8, s8, s88
	v_cvt_pk_bf16_f32 v18, v26, v27
	v_fmamk_f32 v26, v20, 0x30000000, v209
	v_mov_b32_e32 v20, v21
	v_pk_fma_f32 v[38:39], v[42:43], v[38:39], v[42:43] op_sel_hi:[0,1,0]
	v_fmac_f32_e32 v26, 2.0, v20
	v_rcp_f32_e32 v38, v38
	v_rcp_f32_e32 v39, v39
	v_rsq_f32_e32 v27, v26
	s_addc_u32 s9, s9, 0
	v_pk_mul_f32 v[28:29], v[28:29], v[38:39]
	s_nop 0
	v_cvt_pk_bf16_f32 v19, v28, v29
	v_cvt_pk_bf16_f32 v20, v22, v23
	v_cvt_pk_bf16_f32 v21, v24, v25
	global_store_dwordx4 v138, v[18:21], s[8:9]
	s_add_u32 s8, s43, s86
	s_addc_u32 s9, s90, s87
	v_mul_f32_e32 v18, 0xbfb8aa3b, v27
	v_pk_mul_f32 v[20:21], v[14:15], v[18:19] op_sel_hi:[1,0]
	v_pk_mul_f32 v[22:23], v[16:17], v[18:19] op_sel_hi:[1,0]
	v_pk_mul_f32 v[14:15], v[6:7], v[18:19] op_sel_hi:[1,0]
	v_pk_mul_f32 v[16:17], v[8:9], v[18:19] op_sel_hi:[1,0]
	v_exp_f32_e32 v20, v20
	v_exp_f32_e32 v21, v21
	v_exp_f32_e32 v22, v22
	v_exp_f32_e32 v23, v23
	v_exp_f32_e32 v14, v14
	v_exp_f32_e32 v15, v15
	v_exp_f32_e32 v16, v16
	v_exp_f32_e32 v17, v17
	v_pk_fma_f32 v[20:21], v[26:27], v[20:21], v[26:27] op_sel_hi:[0,1,0]
	v_pk_fma_f32 v[22:23], v[26:27], v[22:23], v[26:27] op_sel_hi:[0,1,0]
	v_pk_fma_f32 v[14:15], v[26:27], v[14:15], v[26:27] op_sel_hi:[0,1,0]
	v_pk_fma_f32 v[16:17], v[26:27], v[16:17], v[26:27] op_sel_hi:[0,1,0]
	v_rcp_f32_e32 v20, v20
	v_rcp_f32_e32 v21, v21
	v_rcp_f32_e32 v22, v22
	v_rcp_f32_e32 v23, v23
	v_rcp_f32_e32 v14, v14
	v_rcp_f32_e32 v15, v15
	v_rcp_f32_e32 v16, v16
	v_rcp_f32_e32 v17, v17
	s_add_u32 s8, s8, s88
	s_addc_u32 s9, s9, 0
	v_pk_mul_f32 v[10:11], v[10:11], v[20:21]
	v_pk_mul_f32 v[12:13], v[12:13], v[22:23]
	v_pk_mul_f32 v[6:7], v[2:3], v[14:15]
	v_pk_mul_f32 v[8:9], v[4:5], v[16:17]
	v_cvt_pk_bf16_f32 v2, v10, v11
	v_cvt_pk_bf16_f32 v3, v12, v13
	v_cvt_pk_bf16_f32 v4, v6, v7
	s_andn2_b64 vcc, exec, s[48:49]
	v_cvt_pk_bf16_f32 v5, v8, v9
	global_store_dwordx4 v138, v[2:5], s[8:9]
	s_mov_b64 s[8:9], -1
	s_cbranch_vccnz .LBB0_1869
	s_andn2_b64 vcc, exec, s[44:45]
	s_cbranch_vccnz .LBB0_1868
	s_barrier
	s_branch .LBB0_1868

.LBB0_2453:
	s_lshl_b32 s8, s12, 8
	s_add_i32 s24, s8, s31
	s_ashr_i32 s25, s24, 31
	v_lshl_add_u64 v[174:175], s[24:25], 3, v[170:171]
	global_load_dwordx2 v[202:203], v[174:175], off
	global_load_dwordx2 v[182:183], v[174:175], off offset:128
	s_lshl_b32 s2, s2, 8
	s_or_b32 s8, s2, s33
	s_lshl_b64 s[12:13], s[24:25], 12
	s_add_u32 s2, s60, s12
	s_addc_u32 s21, s14, s13
	s_ashr_i32 s9, s8, 31
	s_lshl_b64 s[8:9], s[8:9], 1
	s_add_u32 s46, s2, s8
	s_addc_u32 s47, s21, s9
	s_add_u32 s2, s34, s12
	s_addc_u32 s12, s35, s13
	s_add_u32 s8, s2, s8
	s_addc_u32 s9, s12, s9
	global_load_dwordx4 v[154:157], v146, s[46:47]
	global_load_dwordx4 v[190:193], v146, s[8:9]
	v_lshl_add_u64 v[176:177], s[46:47], 0, v[146:147]
	s_mov_b32 s13, 0x10000
	v_add_co_u32_e32 v130, vcc, s13, v176
	global_load_dwordx4 v[194:197], v146, s[46:47] offset:256
	s_nop 0
	v_addc_co_u32_e32 v131, vcc, 0, v177, vcc
	global_load_dwordx4 v[142:145], v[130:131], off
	global_load_dwordx4 v[134:137], v[130:131], off offset:256
	global_load_dwordx4 v[198:201], v146, s[8:9] offset:256
	v_lshl_add_u64 v[178:179], s[8:9], 0, v[146:147]
	v_add_co_u32_e32 v180, vcc, s13, v178
	s_flbit_i32_b32 s2, 0
	s_nop 0
	v_addc_co_u32_e32 v181, vcc, 0, v179, vcc
	global_load_dwordx4 v[138:141], v[180:181], off
	global_load_dwordx4 v[130:133], v[180:181], off offset:256
	v_mov_b32_e32 v205, v147
	s_min_u32 s2, s2, 32
	s_sub_i32 s12, 32, s2
	s_mov_b32 s13, 0x30000
	s_waitcnt vmcnt(0)
	v_mov_b32_e32 v204, v203
	v_cvt_f32_u32_e32 v206, v202
	v_lshlrev_b64 v[202:203], s2, v[204:205]
	v_min_u32_e32 v202, 1, v202
	v_or_b32_e32 v202, v203, v202
	v_cvt_f32_u32_e32 v202, v202
	v_fmamk_f32 v203, v206, 0x30000000, v209
	v_ldexp_f32 v202, v202, s12
	v_fmac_f32_e32 v203, 2.0, v202
	v_rsq_f32_e32 v203, v203
	v_lshlrev_b32_e32 v206, 16, v156
	v_mul_f32_e32 v122, v122, v203
	v_mul_f32_e32 v122, 0xbfb8aa3b, v122
	v_exp_f32_e32 v122, v122
	v_mul_f32_e32 v127, v127, v203
	v_mul_f32_e32 v129, v129, v203
	v_mul_f32_e32 v126, v126, v203
	v_mul_f32_e32 v123, v123, v203
	v_mul_f32_e32 v128, v128, v203
	v_mul_f32_e32 v125, v125, v203
	v_mul_f32_e32 v127, 0xbfb8aa3b, v127
	v_mul_f32_e32 v129, 0xbfb8aa3b, v129
	v_mul_f32_e32 v126, 0xbfb8aa3b, v126
	v_mul_f32_e32 v123, 0xbfb8aa3b, v123
	v_mul_f32_e32 v128, 0xbfb8aa3b, v128
	v_mul_f32_e32 v125, 0xbfb8aa3b, v125
	v_exp_f32_e32 v127, v127
	v_exp_f32_e32 v129, v129
	v_exp_f32_e32 v126, v126
	v_exp_f32_e32 v123, v123
	v_exp_f32_e32 v128, v128
	v_exp_f32_e32 v125, v125
	v_add_f32_e32 v122, 1.0, v122
	v_rcp_f32_e32 v122, v122
	v_mul_f32_e32 v124, v124, v203
	v_mul_f32_e32 v124, 0xbfb8aa3b, v124
	v_add_f32_e32 v127, 1.0, v127
	v_add_f32_e32 v129, 1.0, v129
	v_lshlrev_b32_e32 v228, 16, v192
	v_exp_f32_e32 v124, v124
	v_add_f32_e32 v126, 1.0, v126
	v_add_f32_e32 v123, 1.0, v123
	v_add_f32_e32 v128, 1.0, v128
	v_add_f32_e32 v125, 1.0, v125
	v_rcp_f32_e32 v127, v127
	v_rcp_f32_e32 v129, v129
	v_rcp_f32_e32 v126, v126
	v_rcp_f32_e32 v123, v123
	v_rcp_f32_e32 v128, v128
	v_fmac_f32_e32 v206, v122, v228
	v_rcp_f32_e32 v122, v125
	v_mul_f32_e32 v114, v114, v203
	v_mul_f32_e32 v114, 0xbfb8aa3b, v114
	v_lshlrev_b32_e32 v204, 16, v154
	v_and_b32_e32 v154, 0xffff0000, v154
	v_lshlrev_b32_e32 v205, 16, v155
	v_and_b32_e32 v155, 0xffff0000, v155
	v_lshlrev_b32_e32 v202, 16, v190
	v_and_b32_e32 v190, 0xffff0000, v190
	v_lshlrev_b32_e32 v208, 16, v191
	v_and_b32_e32 v191, 0xffff0000, v191
	v_exp_f32_e32 v114, v114
	v_and_b32_e32 v156, 0xffff0000, v156
	v_lshlrev_b32_e32 v207, 16, v157
	v_and_b32_e32 v157, 0xffff0000, v157
	v_and_b32_e32 v192, 0xffff0000, v192
	v_lshlrev_b32_e32 v229, 16, v193
	v_and_b32_e32 v193, 0xffff0000, v193
	v_add_f32_e32 v124, 1.0, v124
	v_fmac_f32_e32 v154, v127, v190
	v_fmac_f32_e32 v155, v129, v191
	v_rcp_f32_e32 v124, v124
	v_fmac_f32_e32 v204, v126, v202
	v_fmac_f32_e32 v156, v123, v192
	v_fmac_f32_e32 v205, v128, v208
	v_fmac_f32_e32 v157, v122, v193
	v_mul_f32_e32 v122, v154, v154
	v_mul_f32_e32 v123, v155, v155
	v_fmac_f32_e32 v122, v204, v204
	v_fmac_f32_e32 v123, v205, v205
	v_mul_f32_e32 v115, v115, v203
	v_add_f32_e32 v122, v122, v123
	v_mul_f32_e32 v123, v156, v156
	v_add_f32_e32 v114, 1.0, v114
	v_mul_f32_e32 v115, 0xbfb8aa3b, v115
	v_fmac_f32_e32 v123, v206, v206
	v_rcp_f32_e32 v114, v114
	v_exp_f32_e32 v115, v115
	v_fmac_f32_e32 v207, v124, v229
	v_add_f32_e32 v122, v123, v122
	v_mul_f32_e32 v123, v157, v157
	v_fmac_f32_e32 v123, v207, v207
	v_add_f32_e32 v126, v123, v122
	v_cvt_pk_bf16_f32 v122, v204, v154
	v_cvt_pk_bf16_f32 v123, v205, v155
	v_lshlrev_b32_e32 v129, 16, v195
	v_and_b32_e32 v154, 0xffff0000, v195
	v_lshlrev_b32_e32 v155, 16, v196
	v_lshlrev_b32_e32 v195, 16, v200
	v_fmac_f32_e32 v155, v114, v195
	v_add_f32_e32 v114, 1.0, v115
	v_mul_f32_e32 v115, v120, v203
	v_mul_f32_e32 v116, v116, v203
	v_mul_f32_e32 v115, 0xbfb8aa3b, v115
	v_mul_f32_e32 v116, 0xbfb8aa3b, v116
	v_rcp_f32_e32 v114, v114
	v_exp_f32_e32 v115, v115
	v_exp_f32_e32 v116, v116
	v_cvt_pk_bf16_f32 v124, v206, v156
	v_and_b32_e32 v156, 0xffff0000, v196
	v_and_b32_e32 v196, 0xffff0000, v200
	v_fmac_f32_e32 v156, v114, v196
	v_add_f32_e32 v114, 1.0, v115
	v_add_f32_e32 v115, 1.0, v116
	v_mul_f32_e32 v116, v121, v203
	v_mul_f32_e32 v117, v117, v203
	v_mul_f32_e32 v116, 0xbfb8aa3b, v116
	v_mul_f32_e32 v117, 0xbfb8aa3b, v117
	v_exp_f32_e32 v116, v116
	v_exp_f32_e32 v117, v117
	v_mul_f32_e32 v119, v119, v203
	v_mul_f32_e32 v119, 0xbfb8aa3b, v119
	v_exp_f32_e32 v119, v119
	v_add_f32_e32 v116, 1.0, v116
	v_add_f32_e32 v117, 1.0, v117
	v_rcp_f32_e32 v116, v116
	v_rcp_f32_e32 v117, v117
	v_lshlrev_b32_e32 v127, 16, v194
	v_and_b32_e32 v128, 0xffff0000, v194
	v_and_b32_e32 v190, 0xffff0000, v197
	v_lshlrev_b32_e32 v191, 16, v198
	v_and_b32_e32 v192, 0xffff0000, v198
	v_and_b32_e32 v194, 0xffff0000, v199
	v_and_b32_e32 v198, 0xffff0000, v201
	v_add_f32_e32 v119, 1.0, v119
	v_rcp_f32_e32 v119, v119
	v_fmac_f32_e32 v154, v116, v194
	v_fmac_f32_e32 v190, v117, v198
	v_mov_b32_e32 v116, v183
	v_mov_b32_e32 v117, v147
	v_mov_b32_e32 v117, v116
	v_fmac_f32_e32 v128, v119, v192
	v_cvt_f32_u32_e32 v119, v182
	v_cvt_f32_u32_e32 v120, v117
	v_mul_f32_e32 v118, v118, v203
	v_mul_f32_e32 v118, 0xbfb8aa3b, v118
	v_fmamk_f32 v119, v119, 0x30000000, v209
	v_fmac_f32_e32 v119, 2.0, v120
	v_rsq_f32_e32 v119, v119
	v_exp_f32_e32 v118, v118
	v_rcp_f32_e32 v114, v114
	v_lshlrev_b32_e32 v193, 16, v199
	v_mul_f32_e32 v106, v106, v119
	v_mul_f32_e32 v106, 0xbfb8aa3b, v106
	v_exp_f32_e32 v106, v106
	v_add_f32_e32 v118, 1.0, v118
	v_mul_f32_e32 v107, v107, v119
	v_rcp_f32_e32 v118, v118
	v_add_f32_e32 v106, 1.0, v106
	v_mul_f32_e32 v107, 0xbfb8aa3b, v107
	v_rcp_f32_e32 v106, v106
	v_exp_f32_e32 v107, v107
	v_fmac_f32_e32 v127, v118, v191
	v_fmac_f32_e32 v129, v114, v193
	v_lshlrev_b32_e32 v191, 16, v143
	v_and_b32_e32 v192, 0xffff0000, v143
	v_lshlrev_b32_e32 v193, 16, v144
	v_lshlrev_b32_e32 v143, 16, v140
	v_fmac_f32_e32 v193, v106, v143
	v_add_f32_e32 v106, 1.0, v107
	v_mul_f32_e32 v107, v112, v119
	v_mul_f32_e32 v108, v108, v119
	v_mul_f32_e32 v107, 0xbfb8aa3b, v107
	v_mul_f32_e32 v108, 0xbfb8aa3b, v108
	v_rcp_f32_e32 v106, v106
	v_exp_f32_e32 v107, v107
	v_exp_f32_e32 v108, v108
	v_and_b32_e32 v194, 0xffff0000, v144
	v_and_b32_e32 v140, 0xffff0000, v140
	v_mul_f32_e32 v110, v110, v119
	v_fmac_f32_e32 v194, v106, v140
	v_add_f32_e32 v106, 1.0, v107
	v_add_f32_e32 v107, 1.0, v108
	v_mul_f32_e32 v108, v113, v119
	v_mul_f32_e32 v109, v109, v119
	v_mul_f32_e32 v110, 0xbfb8aa3b, v110
	v_mul_f32_e32 v108, 0xbfb8aa3b, v108
	v_mul_f32_e32 v109, 0xbfb8aa3b, v109
	v_mul_f32_e32 v98, v98, v119
	v_exp_f32_e32 v110, v110
	v_exp_f32_e32 v108, v108
	v_exp_f32_e32 v109, v109
	v_mul_f32_e32 v98, 0xbfb8aa3b, v98
	v_exp_f32_e32 v98, v98
	v_add_f32_e32 v110, 1.0, v110
	v_mul_f32_e32 v111, v111, v119
	v_add_f32_e32 v108, 1.0, v108
	v_add_f32_e32 v109, 1.0, v109
	v_mul_f32_e32 v99, v99, v119
	v_mul_f32_e32 v111, 0xbfb8aa3b, v111
	v_rcp_f32_e32 v110, v110
	v_rcp_f32_e32 v108, v108
	v_rcp_f32_e32 v109, v109
	v_add_f32_e32 v98, 1.0, v98
	v_mul_f32_e32 v99, 0xbfb8aa3b, v99
	v_exp_f32_e32 v111, v111
	v_rcp_f32_e32 v98, v98
	v_exp_f32_e32 v99, v99
	v_cvt_pk_bf16_f32 v125, v207, v157
	v_mul_f32_e32 v118, v128, v128
	v_cvt_pk_bf16_f32 v114, v127, v128
	v_lshlrev_b32_e32 v120, 16, v142
	v_and_b32_e32 v121, 0xffff0000, v142
	v_and_b32_e32 v196, 0xffff0000, v145
	v_lshlrev_b32_e32 v128, 16, v138
	v_lshlrev_b32_e32 v142, 16, v139
	v_and_b32_e32 v139, 0xffff0000, v139
	v_lshlrev_b32_e32 v144, 16, v141
	v_and_b32_e32 v141, 0xffff0000, v141
	v_fmac_f32_e32 v120, v110, v128
	v_fmac_f32_e32 v192, v108, v139
	v_fmac_f32_e32 v196, v109, v141
	v_lshlrev_b32_e32 v108, 16, v135
	v_and_b32_e32 v109, 0xffff0000, v135
	v_lshlrev_b32_e32 v110, 16, v136
	v_lshlrev_b32_e32 v135, 16, v132
	v_add_f32_e32 v111, 1.0, v111
	v_fmac_f32_e32 v110, v98, v135
	v_add_f32_e32 v98, 1.0, v99
	v_mul_f32_e32 v99, v104, v119
	v_mul_f32_e32 v100, v100, v119
	v_rcp_f32_e32 v111, v111
	v_mul_f32_e32 v99, 0xbfb8aa3b, v99
	v_mul_f32_e32 v100, 0xbfb8aa3b, v100
	v_rcp_f32_e32 v98, v98
	v_exp_f32_e32 v99, v99
	v_exp_f32_e32 v100, v100
	v_and_b32_e32 v138, 0xffff0000, v138
	v_fmac_f32_e32 v121, v111, v138
	v_and_b32_e32 v111, 0xffff0000, v136
	v_and_b32_e32 v132, 0xffff0000, v132
	v_mul_f32_e32 v102, v102, v119
	v_mul_f32_e32 v103, v103, v119
	v_fmac_f32_e32 v111, v98, v132
	v_add_f32_e32 v98, 1.0, v99
	v_add_f32_e32 v99, 1.0, v100
	v_mul_f32_e32 v100, v105, v119
	v_mul_f32_e32 v101, v101, v119
	v_mul_f32_e32 v102, 0xbfb8aa3b, v102
	v_mul_f32_e32 v103, 0xbfb8aa3b, v103
	v_mul_f32_e32 v100, 0xbfb8aa3b, v100
	v_mul_f32_e32 v101, 0xbfb8aa3b, v101
	v_exp_f32_e32 v102, v102
	v_exp_f32_e32 v103, v103
	v_exp_f32_e32 v100, v100
	v_exp_f32_e32 v101, v101
	v_rcp_f32_e32 v106, v106
	v_rcp_f32_e32 v107, v107
	v_add_f32_e32 v102, 1.0, v102
	v_add_f32_e32 v103, 1.0, v103
	v_add_f32_e32 v100, 1.0, v100
	v_add_f32_e32 v101, 1.0, v101
	v_rcp_f32_e32 v115, v115
	v_rcp_f32_e32 v102, v102
	v_rcp_f32_e32 v103, v103
	v_rcp_f32_e32 v98, v98
	v_rcp_f32_e32 v99, v99
	v_rcp_f32_e32 v100, v100
	v_rcp_f32_e32 v101, v101
	v_lshlrev_b32_e32 v195, 16, v145
	v_lshlrev_b32_e32 v157, 16, v197
	v_lshlrev_b32_e32 v197, 16, v201
	v_fmac_f32_e32 v191, v106, v142
	v_fmac_f32_e32 v195, v107, v144
	v_lshlrev_b32_e32 v106, 16, v134
	v_and_b32_e32 v107, 0xffff0000, v134
	v_lshlrev_b32_e32 v112, 16, v137
	v_and_b32_e32 v113, 0xffff0000, v137
	v_lshlrev_b32_e32 v128, 16, v130
	v_and_b32_e32 v130, 0xffff0000, v130
	v_lshlrev_b32_e32 v134, 16, v131
	v_and_b32_e32 v131, 0xffff0000, v131
	v_lshlrev_b32_e32 v136, 16, v133
	v_and_b32_e32 v133, 0xffff0000, v133
	v_fmac_f32_e32 v157, v115, v197
	v_cvt_pk_bf16_f32 v115, v129, v154
	v_cvt_pk_bf16_f32 v116, v155, v156
	v_cvt_pk_bf16_f32 v117, v157, v190
	v_cvt_pk_bf16_f32 v138, v120, v121
	v_cvt_pk_bf16_f32 v139, v191, v192
	v_cvt_pk_bf16_f32 v140, v193, v194
	v_cvt_pk_bf16_f32 v141, v195, v196
	v_fmac_f32_e32 v106, v102, v128
	v_fmac_f32_e32 v107, v103, v130
	v_fmac_f32_e32 v108, v98, v134
	v_fmac_f32_e32 v112, v99, v136
	v_fmac_f32_e32 v109, v100, v131
	v_fmac_f32_e32 v113, v101, v133
	v_cvt_pk_bf16_f32 v134, v106, v107
	v_cvt_pk_bf16_f32 v135, v108, v109
	v_cvt_pk_bf16_f32 v136, v110, v111
	v_cvt_pk_bf16_f32 v137, v112, v113
	global_load_dwordx2 v[182:183], v[174:175], off offset:256
	v_mul_f32_e32 v98, v154, v154
	v_fmac_f32_e32 v118, v127, v127
	v_fmac_f32_e32 v98, v129, v129
	v_mul_f32_e32 v99, v156, v156
	v_add_f32_e32 v98, v118, v98
	v_fmac_f32_e32 v99, v155, v155
	v_add_f32_e32 v100, v99, v98
	v_add_co_u32_e32 v98, vcc, s63, v176
	v_mul_f32_e32 v101, v190, v190
	s_nop 0
	v_addc_co_u32_e32 v99, vcc, 0, v177, vcc
	v_fmac_f32_e32 v101, v157, v157
	v_add_co_u32_e32 v118, vcc, s63, v178
	v_and_b32_e32 v102, 64, v222
	v_add_f32_e32 v100, v101, v100
	v_addc_co_u32_e32 v119, vcc, 0, v179, vcc
	v_xor_b32_e32 v101, 16, v222
	v_add_u32_e32 v102, 64, v102
	v_cmp_lt_i32_e32 vcc, v101, v102
	global_load_dwordx4 v[142:145], v[98:99], off
	global_load_dwordx4 v[154:157], v[118:119], off
	v_cndmask_b32_e32 v101, v222, v101, vcc
	v_add_f32_e32 v100, v126, v100
	v_lshlrev_b32_e32 v129, 2, v101
	ds_bpermute_b32 v101, v129, v100
	s_waitcnt lgkmcnt(0)
	v_add_f32_e32 v128, v100, v101
	v_xor_b32_e32 v100, 32, v222
	v_cmp_lt_i32_e32 vcc, v100, v102
	v_mul_f32_e32 v101, v192, v192
	v_fmac_f32_e32 v101, v191, v191
	v_cndmask_b32_e32 v130, v222, v100, vcc
	v_mul_f32_e32 v100, v121, v121
	v_fmac_f32_e32 v100, v120, v120
	v_add_f32_e32 v100, v100, v101
	v_mul_f32_e32 v101, v194, v194
	v_fmac_f32_e32 v101, v193, v193
	v_add_f32_e32 v100, v101, v100
	v_mul_f32_e32 v101, v196, v196
	v_fmac_f32_e32 v101, v195, v195
	global_load_dwordx4 v[190:193], v[98:99], off offset:256
	global_load_dwordx4 v[194:197], v[118:119], off offset:256
	global_load_dwordx2 v[126:127], v[174:175], off offset:384
	v_add_f32_e32 v100, v101, v100
	v_mul_f32_e32 v101, v107, v107
	v_mul_f32_e32 v102, v109, v109
	v_fmac_f32_e32 v101, v106, v106
	v_fmac_f32_e32 v102, v108, v108
	v_add_f32_e32 v101, v101, v102
	v_mul_f32_e32 v102, v111, v111
	v_fmac_f32_e32 v102, v110, v110
	v_add_f32_e32 v101, v102, v101
	v_mul_f32_e32 v102, v113, v113
	v_add_co_u32_e32 v98, vcc, s13, v176
	v_fmac_f32_e32 v102, v112, v112
	s_nop 0
	v_addc_co_u32_e32 v99, vcc, 0, v177, vcc
	v_add_f32_e32 v101, v102, v101
	v_add_co_u32_e32 v120, vcc, s13, v178
	v_add_f32_e32 v131, v100, v101
	s_nop 0
	v_addc_co_u32_e32 v121, vcc, 0, v179, vcc
	global_load_dwordx4 v[110:113], v[98:99], off
	global_load_dwordx4 v[102:105], v[98:99], off offset:256
	global_load_dwordx4 v[106:109], v[120:121], off
	s_nop 0
	global_load_dwordx4 v[98:101], v[120:121], off offset:256
	global_store_dwordx4 v146, v[122:125], s[8:9]
	global_store_dwordx4 v146, v[114:117], s[8:9] offset:256
	global_store_dwordx4 v[180:181], v[138:141], off
	global_store_dwordx4 v[180:181], v[134:137], off offset:256
	v_mov_b32_e32 v115, v147
	s_mov_b32 s8, 0x80000
	ds_bpermute_b32 v132, v129, v131
	s_waitcnt vmcnt(13)
	v_mov_b32_e32 v114, v183
	v_lshlrev_b64 v[114:115], s2, v[114:115]
	v_min_u32_e32 v114, 1, v114
	v_or_b32_e32 v114, v115, v114
	v_cvt_f32_u32_e32 v116, v182
	v_cvt_f32_u32_e32 v114, v114
	v_fmamk_f32 v115, v116, 0x30000000, v209
	v_ldexp_f32 v114, v114, s12
	v_fmac_f32_e32 v115, 2.0, v114
	v_rsq_f32_e32 v114, v115
	s_waitcnt vmcnt(12)
	v_lshlrev_b32_e32 v123, 16, v144
	v_mul_f32_e32 v90, v90, v114
	v_mul_f32_e32 v90, 0xbfb8aa3b, v90
	v_exp_f32_e32 v90, v90
	v_mul_f32_e32 v91, v91, v114
	v_mul_f32_e32 v91, 0xbfb8aa3b, v91
	v_exp_f32_e32 v91, v91
	v_add_f32_e32 v90, 1.0, v90
	v_rcp_f32_e32 v90, v90
	s_waitcnt vmcnt(11)
	v_lshlrev_b32_e32 v138, 16, v156
	v_mul_f32_e32 v95, v95, v114
	v_mul_f32_e32 v92, v92, v114
	v_fmac_f32_e32 v123, v90, v138
	v_add_f32_e32 v90, 1.0, v91
	v_mul_f32_e32 v91, v96, v114
	v_mul_f32_e32 v95, 0xbfb8aa3b, v95
	v_mul_f32_e32 v91, 0xbfb8aa3b, v91
	v_mul_f32_e32 v92, 0xbfb8aa3b, v92
	v_mul_f32_e32 v82, v82, v114
	v_exp_f32_e32 v95, v95
	v_rcp_f32_e32 v90, v90
	v_exp_f32_e32 v91, v91
	v_exp_f32_e32 v92, v92
	v_mul_f32_e32 v82, 0xbfb8aa3b, v82
	v_exp_f32_e32 v82, v82
	v_and_b32_e32 v124, 0xffff0000, v144
	v_and_b32_e32 v139, 0xffff0000, v156
	v_add_f32_e32 v95, 1.0, v95
	v_fmac_f32_e32 v124, v90, v139
	v_add_f32_e32 v90, 1.0, v91
	v_add_f32_e32 v91, 1.0, v92
	v_mul_f32_e32 v93, v93, v114
	v_mul_f32_e32 v83, v83, v114
	v_rcp_f32_e32 v95, v95
	v_mul_f32_e32 v93, 0xbfb8aa3b, v93
	v_rcp_f32_e32 v91, v91
	v_add_f32_e32 v82, 1.0, v82
	v_mul_f32_e32 v83, 0xbfb8aa3b, v83
	v_exp_f32_e32 v93, v93
	v_rcp_f32_e32 v82, v82
	v_exp_f32_e32 v83, v83
	v_and_b32_e32 v116, 0xffff0000, v142
	v_lshlrev_b32_e32 v125, 16, v145
	v_and_b32_e32 v135, 0xffff0000, v154
	v_lshlrev_b32_e32 v140, 16, v157
	v_fmac_f32_e32 v116, v95, v135
	v_fmac_f32_e32 v125, v91, v140
	s_waitcnt vmcnt(10)
	v_lshlrev_b32_e32 v135, 16, v192
	s_waitcnt vmcnt(9)
	v_lshlrev_b32_e32 v140, 16, v196
	v_add_f32_e32 v93, 1.0, v93
	v_fmac_f32_e32 v135, v82, v140
	v_add_f32_e32 v82, 1.0, v83
	v_mul_f32_e32 v83, v88, v114
	v_mul_f32_e32 v84, v84, v114
	v_rcp_f32_e32 v90, v90
	v_rcp_f32_e32 v93, v93
	v_mul_f32_e32 v83, 0xbfb8aa3b, v83
	v_mul_f32_e32 v84, 0xbfb8aa3b, v84
	v_rcp_f32_e32 v82, v82
	v_exp_f32_e32 v83, v83
	v_exp_f32_e32 v84, v84
	v_lshlrev_b32_e32 v117, 16, v143
	v_and_b32_e32 v133, 0xffff0000, v145
	v_lshlrev_b32_e32 v136, 16, v155
	v_and_b32_e32 v141, 0xffff0000, v157
	v_mul_f32_e32 v94, v94, v114
	v_fmac_f32_e32 v117, v90, v136
	v_fmac_f32_e32 v133, v93, v141
	v_and_b32_e32 v136, 0xffff0000, v192
	v_and_b32_e32 v141, 0xffff0000, v196
	v_mul_f32_e32 v94, 0xbfb8aa3b, v94
	v_fmac_f32_e32 v136, v82, v141
	v_add_f32_e32 v82, 1.0, v83
	v_add_f32_e32 v83, 1.0, v84
	v_mul_f32_e32 v84, v89, v114
	v_mul_f32_e32 v85, v85, v114
	v_exp_f32_e32 v94, v94
	v_mul_f32_e32 v84, 0xbfb8aa3b, v84
	v_mul_f32_e32 v85, 0xbfb8aa3b, v85
	v_exp_f32_e32 v84, v84
	v_exp_f32_e32 v85, v85
	v_mul_f32_e32 v86, v86, v114
	v_mul_f32_e32 v87, v87, v114
	v_add_f32_e32 v94, 1.0, v94
	v_mul_f32_e32 v86, 0xbfb8aa3b, v86
	v_mul_f32_e32 v87, 0xbfb8aa3b, v87
	v_rcp_f32_e32 v94, v94
	v_exp_f32_e32 v86, v86
	v_exp_f32_e32 v87, v87
	v_add_f32_e32 v84, 1.0, v84
	v_add_f32_e32 v85, 1.0, v85
	v_rcp_f32_e32 v84, v84
	v_rcp_f32_e32 v85, v85
	v_lshlrev_b32_e32 v115, 16, v142
	v_lshlrev_b32_e32 v134, 16, v154
	v_and_b32_e32 v122, 0xffff0000, v143
	v_fmac_f32_e32 v115, v94, v134
	v_and_b32_e32 v134, 0xffff0000, v191
	v_and_b32_e32 v138, 0xffff0000, v193
	v_and_b32_e32 v139, 0xffff0000, v195
	v_and_b32_e32 v143, 0xffff0000, v197
	v_add_f32_e32 v86, 1.0, v86
	v_add_f32_e32 v87, 1.0, v87
	v_rcp_f32_e32 v86, v86
	v_rcp_f32_e32 v87, v87
	v_fmac_f32_e32 v134, v84, v139
	v_fmac_f32_e32 v138, v85, v143
	s_waitcnt vmcnt(8)
	v_mov_b32_e32 v84, v127
	v_mov_b32_e32 v85, v147
	v_mov_b32_e32 v85, v84
	v_mul_f32_e32 v94, v116, v116
	v_mul_f32_e32 v92, v97, v114
	v_fmac_f32_e32 v94, v115, v115
	v_cvt_pk_bf16_f32 v90, v115, v116
	v_lshlrev_b32_e32 v96, 16, v190
	v_and_b32_e32 v97, 0xffff0000, v190
	v_lshlrev_b32_e32 v115, 16, v194
	v_and_b32_e32 v116, 0xffff0000, v194
	v_fmac_f32_e32 v96, v86, v115
	v_fmac_f32_e32 v97, v87, v116
	v_cvt_f32_u32_e32 v86, v126
	v_cvt_f32_u32_e32 v87, v85
	s_waitcnt vmcnt(7)
	v_lshlrev_b32_e32 v126, 16, v111
	v_and_b32_e32 v127, 0xffff0000, v111
	v_fmamk_f32 v86, v86, 0x30000000, v209
	v_fmac_f32_e32 v86, 2.0, v87
	v_rsq_f32_e32 v86, v86
	v_lshlrev_b32_e32 v139, 16, v112
	s_waitcnt vmcnt(5)
	v_lshlrev_b32_e32 v111, 16, v108
	v_mul_f32_e32 v92, 0xbfb8aa3b, v92
	v_mul_f32_e32 v74, v74, v86
	v_mul_f32_e32 v74, 0xbfb8aa3b, v74
	v_exp_f32_e32 v74, v74
	v_mul_f32_e32 v75, v75, v86
	v_mul_f32_e32 v75, 0xbfb8aa3b, v75
	v_exp_f32_e32 v75, v75
	v_add_f32_e32 v74, 1.0, v74
	v_rcp_f32_e32 v74, v74
	v_mul_f32_e32 v76, v76, v86
	v_mul_f32_e32 v76, 0xbfb8aa3b, v76
	v_exp_f32_e32 v76, v76
	v_fmac_f32_e32 v139, v74, v111
	v_add_f32_e32 v74, 1.0, v75
	v_mul_f32_e32 v75, v80, v86
	v_mul_f32_e32 v75, 0xbfb8aa3b, v75
	v_rcp_f32_e32 v74, v74
	v_exp_f32_e32 v75, v75
	v_and_b32_e32 v140, 0xffff0000, v112
	v_and_b32_e32 v108, 0xffff0000, v108
	v_exp_f32_e32 v92, v92
	v_mul_f32_e32 v78, v78, v86
	v_fmac_f32_e32 v140, v74, v108
	v_add_f32_e32 v74, 1.0, v75
	v_add_f32_e32 v75, 1.0, v76
	v_mul_f32_e32 v76, v81, v86
	v_mul_f32_e32 v77, v77, v86
	v_mul_f32_e32 v78, 0xbfb8aa3b, v78
	v_mul_f32_e32 v76, 0xbfb8aa3b, v76
	v_mul_f32_e32 v77, 0xbfb8aa3b, v77
	v_mul_f32_e32 v66, v66, v86
	v_exp_f32_e32 v78, v78
	v_exp_f32_e32 v76, v76
	v_exp_f32_e32 v77, v77
	v_mul_f32_e32 v66, 0xbfb8aa3b, v66
	v_exp_f32_e32 v66, v66
	v_add_f32_e32 v92, 1.0, v92
	v_rcp_f32_e32 v92, v92
	v_rcp_f32_e32 v83, v83
	v_add_f32_e32 v78, 1.0, v78
	v_mul_f32_e32 v79, v79, v86
	v_add_f32_e32 v76, 1.0, v76
	v_add_f32_e32 v77, 1.0, v77
	v_mul_f32_e32 v67, v67, v86
	v_mul_f32_e32 v79, 0xbfb8aa3b, v79
	v_rcp_f32_e32 v78, v78
	v_rcp_f32_e32 v76, v76
	v_rcp_f32_e32 v77, v77
	v_add_f32_e32 v66, 1.0, v66
	v_mul_f32_e32 v67, 0xbfb8aa3b, v67
	v_and_b32_e32 v137, 0xffff0000, v155
	v_exp_f32_e32 v79, v79
	v_rcp_f32_e32 v66, v66
	v_exp_f32_e32 v67, v67
	v_fmac_f32_e32 v122, v92, v137
	v_lshlrev_b32_e32 v137, 16, v193
	v_lshlrev_b32_e32 v142, 16, v197
	v_fmac_f32_e32 v137, v83, v142
	v_lshlrev_b32_e32 v88, 16, v110
	v_and_b32_e32 v89, 0xffff0000, v110
	v_and_b32_e32 v142, 0xffff0000, v113
	v_lshlrev_b32_e32 v87, 16, v106
	v_lshlrev_b32_e32 v110, 16, v107
	v_and_b32_e32 v107, 0xffff0000, v107
	v_lshlrev_b32_e32 v112, 16, v109
	v_and_b32_e32 v109, 0xffff0000, v109
	v_fmac_f32_e32 v88, v78, v87
	v_fmac_f32_e32 v127, v76, v107
	v_fmac_f32_e32 v142, v77, v109
	v_lshlrev_b32_e32 v76, 16, v103
	v_and_b32_e32 v77, 0xffff0000, v103
	v_lshlrev_b32_e32 v78, 16, v104
	s_waitcnt vmcnt(4)
	v_lshlrev_b32_e32 v103, 16, v100
	v_add_f32_e32 v79, 1.0, v79
	v_fmac_f32_e32 v78, v66, v103
	v_add_f32_e32 v66, 1.0, v67
	v_mul_f32_e32 v67, v72, v86
	v_mul_f32_e32 v68, v68, v86
	v_rcp_f32_e32 v79, v79
	v_mul_f32_e32 v67, 0xbfb8aa3b, v67
	v_mul_f32_e32 v68, 0xbfb8aa3b, v68
	v_rcp_f32_e32 v66, v66
	v_exp_f32_e32 v67, v67
	v_exp_f32_e32 v68, v68
	v_and_b32_e32 v106, 0xffff0000, v106
	v_fmac_f32_e32 v89, v79, v106
	v_and_b32_e32 v79, 0xffff0000, v104
	v_and_b32_e32 v100, 0xffff0000, v100
	v_mul_f32_e32 v70, v70, v86
	v_mul_f32_e32 v71, v71, v86
	v_fmac_f32_e32 v79, v66, v100
	v_add_f32_e32 v66, 1.0, v67
	v_add_f32_e32 v67, 1.0, v68
	v_mul_f32_e32 v68, v73, v86
	v_mul_f32_e32 v69, v69, v86
	v_mul_f32_e32 v70, 0xbfb8aa3b, v70
	v_mul_f32_e32 v71, 0xbfb8aa3b, v71
	v_mul_f32_e32 v68, 0xbfb8aa3b, v68
	v_mul_f32_e32 v69, 0xbfb8aa3b, v69
	v_exp_f32_e32 v70, v70
	v_exp_f32_e32 v71, v71
	v_exp_f32_e32 v68, v68
	v_exp_f32_e32 v69, v69
	v_rcp_f32_e32 v74, v74
	v_rcp_f32_e32 v75, v75
	v_add_f32_e32 v70, 1.0, v70
	v_add_f32_e32 v71, 1.0, v71
	v_add_f32_e32 v68, 1.0, v68
	v_add_f32_e32 v69, 1.0, v69
	v_rcp_f32_e32 v82, v82
	v_rcp_f32_e32 v70, v70
	v_rcp_f32_e32 v71, v71
	v_rcp_f32_e32 v66, v66
	v_rcp_f32_e32 v67, v67
	v_rcp_f32_e32 v68, v68
	v_rcp_f32_e32 v69, v69
	v_mul_f32_e32 v95, v122, v122
	v_lshlrev_b32_e32 v141, 16, v113
	v_fmac_f32_e32 v95, v117, v117
	v_cvt_pk_bf16_f32 v91, v117, v122
	v_lshlrev_b32_e32 v122, 16, v191
	v_lshlrev_b32_e32 v117, 16, v195
	v_fmac_f32_e32 v126, v74, v110
	v_fmac_f32_e32 v141, v75, v112
	v_lshlrev_b32_e32 v74, 16, v102
	v_and_b32_e32 v75, 0xffff0000, v102
	v_lshlrev_b32_e32 v80, 16, v105
	v_and_b32_e32 v81, 0xffff0000, v105
	v_lshlrev_b32_e32 v87, 16, v98
	v_and_b32_e32 v98, 0xffff0000, v98
	v_lshlrev_b32_e32 v102, 16, v99
	v_and_b32_e32 v99, 0xffff0000, v99
	v_lshlrev_b32_e32 v104, 16, v101
	v_and_b32_e32 v101, 0xffff0000, v101
	v_cvt_pk_bf16_f32 v92, v123, v124
	v_cvt_pk_bf16_f32 v93, v125, v133
	v_fmac_f32_e32 v122, v82, v117
	v_cvt_pk_bf16_f32 v82, v96, v97
	v_cvt_pk_bf16_f32 v83, v122, v134
	v_cvt_pk_bf16_f32 v84, v135, v136
	v_cvt_pk_bf16_f32 v85, v137, v138
	v_cvt_pk_bf16_f32 v106, v88, v89
	v_cvt_pk_bf16_f32 v107, v126, v127
	v_cvt_pk_bf16_f32 v108, v139, v140
	v_cvt_pk_bf16_f32 v109, v141, v142
	v_fmac_f32_e32 v74, v70, v87
	v_fmac_f32_e32 v75, v71, v98
	v_fmac_f32_e32 v76, v66, v102
	v_fmac_f32_e32 v80, v67, v104
	v_fmac_f32_e32 v77, v68, v99
	v_fmac_f32_e32 v81, v69, v101
	v_cvt_pk_bf16_f32 v110, v74, v75
	v_cvt_pk_bf16_f32 v111, v76, v77
	v_cvt_pk_bf16_f32 v112, v78, v79
	v_cvt_pk_bf16_f32 v113, v80, v81
	global_load_dwordx2 v[104:105], v[174:175], off offset:1024
	v_mul_f32_e32 v67, v124, v124
	v_add_f32_e32 v66, v94, v95
	v_fmac_f32_e32 v67, v123, v123
	v_add_f32_e32 v66, v67, v66
	v_mul_f32_e32 v67, v133, v133
	v_fmac_f32_e32 v67, v125, v125
	v_add_f32_e32 v68, v67, v66
	v_add_co_u32_e32 v66, vcc, s8, v176
	v_mul_f32_e32 v70, v134, v134
	s_nop 0
	v_addc_co_u32_e32 v67, vcc, 0, v177, vcc
	v_add_co_u32_e32 v86, vcc, s8, v178
	global_load_dwordx4 v[114:117], v[66:67], off
	s_nop 0
	v_addc_co_u32_e32 v87, vcc, 0, v179, vcc
	v_fmac_f32_e32 v70, v122, v122
	global_load_dwordx4 v[122:125], v[86:87], off
	v_mul_f32_e32 v69, v97, v97
	v_fmac_f32_e32 v69, v96, v96
	v_add_f32_e32 v69, v69, v70
	v_mul_f32_e32 v70, v136, v136
	v_fmac_f32_e32 v70, v135, v135
	v_add_f32_e32 v69, v70, v69
	v_mul_f32_e32 v70, v138, v138
	v_fmac_f32_e32 v70, v137, v137
	v_lshlrev_b32_e32 v101, 2, v130
	s_waitcnt lgkmcnt(0)
	v_add_f32_e32 v97, v131, v132
	global_load_dwordx4 v[130:133], v[66:67], off offset:256
	global_load_dwordx4 v[134:137], v[86:87], off offset:256
	global_load_dwordx2 v[94:95], v[174:175], off offset:1152
	v_add_f32_e32 v69, v70, v69
	v_add_f32_e32 v68, v68, v69
	ds_bpermute_b32 v69, v129, v68
	v_mul_f32_e32 v70, v77, v77
	v_fmac_f32_e32 v70, v76, v76
	s_mov_b32 s8, 0x90000
	v_add_co_u32_e32 v66, vcc, s8, v176
	s_waitcnt lgkmcnt(0)
	v_add_f32_e32 v99, v68, v69
	v_mul_f32_e32 v68, v89, v89
	v_mul_f32_e32 v69, v127, v127
	v_fmac_f32_e32 v68, v88, v88
	v_fmac_f32_e32 v69, v126, v126
	v_add_f32_e32 v68, v68, v69
	v_mul_f32_e32 v69, v140, v140
	v_fmac_f32_e32 v69, v139, v139
	v_add_f32_e32 v68, v69, v68
	v_mul_f32_e32 v69, v142, v142
	v_fmac_f32_e32 v69, v141, v141
	v_add_f32_e32 v68, v69, v68
	v_mul_f32_e32 v69, v75, v75
	v_fmac_f32_e32 v69, v74, v74
	v_add_f32_e32 v69, v69, v70
	v_mul_f32_e32 v70, v79, v79
	v_fmac_f32_e32 v70, v78, v78
	v_add_f32_e32 v69, v70, v69
	v_mul_f32_e32 v70, v81, v81
	v_fmac_f32_e32 v70, v80, v80
	v_addc_co_u32_e32 v67, vcc, 0, v177, vcc
	v_add_f32_e32 v69, v70, v69
	v_add_co_u32_e32 v88, vcc, s8, v178
	v_add_f32_e32 v102, v68, v69
	s_nop 0
	v_addc_co_u32_e32 v89, vcc, 0, v179, vcc
	global_load_dwordx4 v[78:81], v[66:67], off
	global_load_dwordx4 v[70:73], v[66:67], off offset:256
	global_load_dwordx4 v[74:77], v[88:89], off
	s_nop 0
	global_load_dwordx4 v[66:69], v[88:89], off offset:256
	global_store_dwordx4 v[118:119], v[90:93], off
	global_store_dwordx4 v[118:119], v[82:85], off offset:256
	global_store_dwordx4 v[120:121], v[106:109], off
	global_store_dwordx4 v[120:121], v[110:113], off offset:256
	v_mov_b32_e32 v83, v147
	s_mov_b32 s8, 0xa0000
	ds_bpermute_b32 v103, v129, v102
	ds_bpermute_b32 v96, v101, v128
	ds_bpermute_b32 v98, v101, v97
	ds_bpermute_b32 v100, v101, v99
	s_waitcnt vmcnt(13)
	v_mov_b32_e32 v82, v105
	v_lshlrev_b64 v[82:83], s2, v[82:83]
	v_min_u32_e32 v82, 1, v82
	v_or_b32_e32 v82, v83, v82
	v_cvt_f32_u32_e32 v84, v104
	v_cvt_f32_u32_e32 v82, v82
	v_fmamk_f32 v83, v84, 0x30000000, v209
	v_ldexp_f32 v82, v82, s12
	v_fmac_f32_e32 v83, 2.0, v82
	v_rsq_f32_e32 v82, v83
	s_waitcnt vmcnt(12)
	v_lshlrev_b32_e32 v91, 16, v116
	v_mul_f32_e32 v58, v58, v82
	v_mul_f32_e32 v58, 0xbfb8aa3b, v58
	v_exp_f32_e32 v58, v58
	v_mul_f32_e32 v59, v59, v82
	v_mul_f32_e32 v59, 0xbfb8aa3b, v59
	v_exp_f32_e32 v59, v59
	v_add_f32_e32 v58, 1.0, v58
	v_rcp_f32_e32 v58, v58
	s_waitcnt vmcnt(11)
	v_lshlrev_b32_e32 v109, 16, v124
	v_mul_f32_e32 v60, v60, v82
	v_mul_f32_e32 v60, 0xbfb8aa3b, v60
	v_fmac_f32_e32 v91, v58, v109
	v_add_f32_e32 v58, 1.0, v59
	v_mul_f32_e32 v59, v64, v82
	v_mul_f32_e32 v59, 0xbfb8aa3b, v59
	v_rcp_f32_e32 v58, v58
	v_exp_f32_e32 v59, v59
	v_exp_f32_e32 v60, v60
	v_and_b32_e32 v92, 0xffff0000, v116
	v_and_b32_e32 v110, 0xffff0000, v124
	v_fmac_f32_e32 v92, v58, v110
	v_add_f32_e32 v58, 1.0, v59
	v_add_f32_e32 v59, 1.0, v60
	v_mul_f32_e32 v60, v65, v82
	v_mul_f32_e32 v62, v62, v82
	v_mul_f32_e32 v63, v63, v82
	v_mul_f32_e32 v60, 0xbfb8aa3b, v60
	v_mul_f32_e32 v62, 0xbfb8aa3b, v62
	v_mul_f32_e32 v63, 0xbfb8aa3b, v63
	v_exp_f32_e32 v60, v60
	v_mul_f32_e32 v50, v50, v82
	v_exp_f32_e32 v62, v62
	v_exp_f32_e32 v63, v63
	v_mul_f32_e32 v50, 0xbfb8aa3b, v50
	v_exp_f32_e32 v50, v50
	v_add_f32_e32 v60, 1.0, v60
	v_add_f32_e32 v62, 1.0, v62
	v_add_f32_e32 v63, 1.0, v63
	v_mul_f32_e32 v61, v61, v82
	v_rcp_f32_e32 v60, v60
	v_mul_f32_e32 v51, v51, v82
	v_rcp_f32_e32 v62, v62
	v_rcp_f32_e32 v63, v63
	v_rcp_f32_e32 v58, v58
	v_mul_f32_e32 v61, 0xbfb8aa3b, v61
	v_rcp_f32_e32 v59, v59
	v_add_f32_e32 v50, 1.0, v50
	v_mul_f32_e32 v51, 0xbfb8aa3b, v51
	v_exp_f32_e32 v61, v61
	v_rcp_f32_e32 v50, v50
	v_exp_f32_e32 v51, v51
	v_and_b32_e32 v90, 0xffff0000, v115
	v_and_b32_e32 v108, 0xffff0000, v123
	v_lshlrev_b32_e32 v83, 16, v114
	v_and_b32_e32 v84, 0xffff0000, v114
	v_lshlrev_b32_e32 v85, 16, v115
	v_lshlrev_b32_e32 v93, 16, v117
	v_lshlrev_b32_e32 v105, 16, v122
	v_and_b32_e32 v106, 0xffff0000, v122
	v_lshlrev_b32_e32 v107, 16, v123
	v_lshlrev_b32_e32 v111, 16, v125
	v_fmac_f32_e32 v90, v60, v108
	v_fmac_f32_e32 v83, v62, v105
	v_fmac_f32_e32 v84, v63, v106
	v_fmac_f32_e32 v85, v58, v107
	v_fmac_f32_e32 v93, v59, v111
	v_mul_f32_e32 v63, v90, v90
	v_cvt_pk_bf16_f32 v58, v83, v84
	v_cvt_pk_bf16_f32 v59, v85, v90
	s_waitcnt vmcnt(10)
	v_lshlrev_b32_e32 v90, 16, v132
	s_waitcnt vmcnt(9)
	v_lshlrev_b32_e32 v111, 16, v136
	v_add_f32_e32 v61, 1.0, v61
	v_fmac_f32_e32 v90, v50, v111
	v_add_f32_e32 v50, 1.0, v51
	v_mul_f32_e32 v51, v56, v82
	v_mul_f32_e32 v52, v52, v82
	v_rcp_f32_e32 v61, v61
	v_mul_f32_e32 v51, 0xbfb8aa3b, v51
	v_mul_f32_e32 v52, 0xbfb8aa3b, v52
	v_rcp_f32_e32 v50, v50
	v_exp_f32_e32 v51, v51
	v_exp_f32_e32 v52, v52
	v_and_b32_e32 v104, 0xffff0000, v117
	v_and_b32_e32 v112, 0xffff0000, v125
	v_fmac_f32_e32 v104, v61, v112
	v_and_b32_e32 v105, 0xffff0000, v132
	v_and_b32_e32 v112, 0xffff0000, v136
	v_fmac_f32_e32 v105, v50, v112
	v_add_f32_e32 v50, 1.0, v51
	v_add_f32_e32 v51, 1.0, v52
	v_mul_f32_e32 v52, v57, v82
	v_mul_f32_e32 v53, v53, v82
	v_mul_f32_e32 v52, 0xbfb8aa3b, v52
	v_mul_f32_e32 v53, 0xbfb8aa3b, v53
	v_exp_f32_e32 v52, v52
	v_exp_f32_e32 v53, v53
	v_mul_f32_e32 v54, v54, v82
	v_mul_f32_e32 v55, v55, v82
	v_mul_f32_e32 v54, 0xbfb8aa3b, v54
	v_mul_f32_e32 v55, 0xbfb8aa3b, v55
	v_exp_f32_e32 v54, v54
	v_exp_f32_e32 v55, v55
	v_add_f32_e32 v52, 1.0, v52
	v_add_f32_e32 v53, 1.0, v53
	v_rcp_f32_e32 v52, v52
	v_rcp_f32_e32 v53, v53
	v_mul_f32_e32 v62, v84, v84
	v_and_b32_e32 v84, 0xffff0000, v131
	v_and_b32_e32 v107, 0xffff0000, v133
	v_and_b32_e32 v110, 0xffff0000, v135
	v_and_b32_e32 v114, 0xffff0000, v137
	v_add_f32_e32 v54, 1.0, v54
	v_add_f32_e32 v55, 1.0, v55
	v_rcp_f32_e32 v54, v54
	v_rcp_f32_e32 v55, v55
	v_fmac_f32_e32 v84, v52, v110
	v_fmac_f32_e32 v107, v53, v114
	s_waitcnt vmcnt(8)
	v_mov_b32_e32 v52, v95
	v_mov_b32_e32 v53, v147
	v_mov_b32_e32 v53, v52
	v_fmac_f32_e32 v63, v85, v85
	v_lshlrev_b32_e32 v64, 16, v130
	v_and_b32_e32 v65, 0xffff0000, v130
	v_lshlrev_b32_e32 v85, 16, v134
	v_and_b32_e32 v108, 0xffff0000, v134
	v_fmac_f32_e32 v64, v54, v85
	v_fmac_f32_e32 v65, v55, v108
	v_cvt_f32_u32_e32 v54, v94
	v_cvt_f32_u32_e32 v55, v53
	v_rcp_f32_e32 v50, v50
	v_fmac_f32_e32 v62, v83, v83
	v_fmamk_f32 v54, v54, 0x30000000, v209
	v_fmac_f32_e32 v54, 2.0, v55
	v_rsq_f32_e32 v54, v54
	v_lshlrev_b32_e32 v83, 16, v131
	v_lshlrev_b32_e32 v109, 16, v135
	v_fmac_f32_e32 v83, v50, v109
	v_mul_f32_e32 v42, v42, v54
	v_mul_f32_e32 v42, 0xbfb8aa3b, v42
	v_exp_f32_e32 v42, v42
	v_mul_f32_e32 v43, v43, v54
	v_mul_f32_e32 v43, 0xbfb8aa3b, v43
	v_exp_f32_e32 v43, v43
	v_add_f32_e32 v42, 1.0, v42
	v_rcp_f32_e32 v42, v42
	s_waitcnt vmcnt(7)
	v_lshlrev_b32_e32 v108, 16, v79
	v_and_b32_e32 v109, 0xffff0000, v79
	v_lshlrev_b32_e32 v110, 16, v80
	s_waitcnt vmcnt(5)
	v_lshlrev_b32_e32 v79, 16, v76
	v_fmac_f32_e32 v110, v42, v79
	v_add_f32_e32 v42, 1.0, v43
	v_mul_f32_e32 v43, v48, v54
	v_mul_f32_e32 v44, v44, v54
	v_mul_f32_e32 v43, 0xbfb8aa3b, v43
	v_mul_f32_e32 v44, 0xbfb8aa3b, v44
	v_rcp_f32_e32 v42, v42
	v_exp_f32_e32 v43, v43
	v_exp_f32_e32 v44, v44
	v_and_b32_e32 v111, 0xffff0000, v80
	v_and_b32_e32 v76, 0xffff0000, v76
	v_mul_f32_e32 v46, v46, v54
	v_fmac_f32_e32 v111, v42, v76
	v_add_f32_e32 v42, 1.0, v43
	v_add_f32_e32 v43, 1.0, v44
	v_mul_f32_e32 v44, v49, v54
	v_mul_f32_e32 v45, v45, v54
	v_mul_f32_e32 v46, 0xbfb8aa3b, v46
	v_mul_f32_e32 v44, 0xbfb8aa3b, v44
	v_mul_f32_e32 v45, 0xbfb8aa3b, v45
	v_mul_f32_e32 v34, v34, v54
	v_exp_f32_e32 v46, v46
	v_exp_f32_e32 v44, v44
	v_exp_f32_e32 v45, v45
	v_mul_f32_e32 v34, 0xbfb8aa3b, v34
	v_exp_f32_e32 v34, v34
	v_rcp_f32_e32 v51, v51
	v_add_f32_e32 v46, 1.0, v46
	v_mul_f32_e32 v47, v47, v54
	v_add_f32_e32 v44, 1.0, v44
	v_add_f32_e32 v45, 1.0, v45
	v_mul_f32_e32 v35, v35, v54
	v_mul_f32_e32 v47, 0xbfb8aa3b, v47
	v_rcp_f32_e32 v46, v46
	v_rcp_f32_e32 v44, v44
	v_rcp_f32_e32 v45, v45
	v_add_f32_e32 v34, 1.0, v34
	v_mul_f32_e32 v35, 0xbfb8aa3b, v35
	v_exp_f32_e32 v47, v47
	v_rcp_f32_e32 v34, v34
	v_exp_f32_e32 v35, v35
	v_lshlrev_b32_e32 v106, 16, v133
	v_lshlrev_b32_e32 v113, 16, v137
	v_fmac_f32_e32 v106, v51, v113
	v_lshlrev_b32_e32 v56, 16, v78
	v_and_b32_e32 v57, 0xffff0000, v78
	v_and_b32_e32 v113, 0xffff0000, v81
	v_lshlrev_b32_e32 v55, 16, v74
	v_lshlrev_b32_e32 v78, 16, v75
	v_and_b32_e32 v75, 0xffff0000, v75
	v_lshlrev_b32_e32 v80, 16, v77
	v_and_b32_e32 v77, 0xffff0000, v77
	v_fmac_f32_e32 v56, v46, v55
	v_fmac_f32_e32 v109, v44, v75
	v_fmac_f32_e32 v113, v45, v77
	v_lshlrev_b32_e32 v44, 16, v71
	v_and_b32_e32 v45, 0xffff0000, v71
	v_lshlrev_b32_e32 v46, 16, v72
	s_waitcnt vmcnt(4)
	v_lshlrev_b32_e32 v71, 16, v68
	v_add_f32_e32 v47, 1.0, v47
	v_fmac_f32_e32 v46, v34, v71
	v_add_f32_e32 v34, 1.0, v35
	v_mul_f32_e32 v35, v40, v54
	v_mul_f32_e32 v36, v36, v54
	v_rcp_f32_e32 v47, v47
	v_mul_f32_e32 v35, 0xbfb8aa3b, v35
	v_mul_f32_e32 v36, 0xbfb8aa3b, v36
	v_rcp_f32_e32 v34, v34
	v_exp_f32_e32 v35, v35
	v_exp_f32_e32 v36, v36
	v_and_b32_e32 v74, 0xffff0000, v74
	v_fmac_f32_e32 v57, v47, v74
	v_and_b32_e32 v47, 0xffff0000, v72
	v_and_b32_e32 v68, 0xffff0000, v68
	v_mul_f32_e32 v38, v38, v54
	v_mul_f32_e32 v39, v39, v54
	v_fmac_f32_e32 v47, v34, v68
	v_add_f32_e32 v34, 1.0, v35
	v_add_f32_e32 v35, 1.0, v36
	v_mul_f32_e32 v36, v41, v54
	v_mul_f32_e32 v37, v37, v54
	v_mul_f32_e32 v38, 0xbfb8aa3b, v38
	v_mul_f32_e32 v39, 0xbfb8aa3b, v39
	v_mul_f32_e32 v36, 0xbfb8aa3b, v36
	v_mul_f32_e32 v37, 0xbfb8aa3b, v37
	v_exp_f32_e32 v38, v38
	v_exp_f32_e32 v39, v39
	v_exp_f32_e32 v36, v36
	v_exp_f32_e32 v37, v37
	v_rcp_f32_e32 v42, v42
	v_rcp_f32_e32 v43, v43
	v_add_f32_e32 v38, 1.0, v38
	v_add_f32_e32 v39, 1.0, v39
	v_add_f32_e32 v36, 1.0, v36
	v_add_f32_e32 v37, 1.0, v37
	v_rcp_f32_e32 v38, v38
	v_rcp_f32_e32 v39, v39
	v_rcp_f32_e32 v34, v34
	v_rcp_f32_e32 v35, v35
	v_rcp_f32_e32 v36, v36
	v_rcp_f32_e32 v37, v37
	v_lshlrev_b32_e32 v112, 16, v81
	v_fmac_f32_e32 v108, v42, v78
	v_fmac_f32_e32 v112, v43, v80
	v_lshlrev_b32_e32 v42, 16, v70
	v_and_b32_e32 v43, 0xffff0000, v70
	v_lshlrev_b32_e32 v48, 16, v73
	v_and_b32_e32 v49, 0xffff0000, v73
	v_lshlrev_b32_e32 v55, 16, v66
	v_and_b32_e32 v66, 0xffff0000, v66
	v_lshlrev_b32_e32 v70, 16, v67
	v_and_b32_e32 v67, 0xffff0000, v67
	v_lshlrev_b32_e32 v72, 16, v69
	v_and_b32_e32 v69, 0xffff0000, v69
	v_cvt_pk_bf16_f32 v60, v91, v92
	v_cvt_pk_bf16_f32 v61, v93, v104
	v_cvt_pk_bf16_f32 v50, v64, v65
	v_cvt_pk_bf16_f32 v51, v83, v84
	v_cvt_pk_bf16_f32 v52, v90, v105
	v_cvt_pk_bf16_f32 v53, v106, v107
	v_cvt_pk_bf16_f32 v74, v56, v57
	v_cvt_pk_bf16_f32 v75, v108, v109
	v_cvt_pk_bf16_f32 v76, v110, v111
	v_cvt_pk_bf16_f32 v77, v112, v113
	v_fmac_f32_e32 v42, v38, v55
	v_fmac_f32_e32 v43, v39, v66
	v_fmac_f32_e32 v44, v34, v70
	v_fmac_f32_e32 v48, v35, v72
	v_fmac_f32_e32 v45, v36, v67
	v_fmac_f32_e32 v49, v37, v69
	v_cvt_pk_bf16_f32 v70, v42, v43
	v_cvt_pk_bf16_f32 v71, v44, v45
	v_cvt_pk_bf16_f32 v72, v46, v47
	v_cvt_pk_bf16_f32 v73, v48, v49
	global_load_dwordx2 v[94:95], v[174:175], off offset:1280
	v_mul_f32_e32 v35, v92, v92
	v_add_f32_e32 v34, v62, v63
	v_fmac_f32_e32 v35, v91, v91
	v_add_f32_e32 v34, v35, v34
	v_mul_f32_e32 v35, v104, v104
	v_fmac_f32_e32 v35, v93, v93
	v_add_f32_e32 v36, v35, v34
	v_add_co_u32_e32 v34, vcc, s8, v176
	v_mul_f32_e32 v38, v84, v84
	s_nop 0
	v_addc_co_u32_e32 v35, vcc, 0, v177, vcc
	v_add_co_u32_e32 v54, vcc, s8, v178
	global_load_dwordx4 v[78:81], v[34:35], off
	s_nop 0
	v_addc_co_u32_e32 v55, vcc, 0, v179, vcc
	v_fmac_f32_e32 v38, v83, v83
	global_load_dwordx4 v[82:85], v[54:55], off
	v_mul_f32_e32 v37, v65, v65
	v_fmac_f32_e32 v37, v64, v64
	v_add_f32_e32 v37, v37, v38
	v_mul_f32_e32 v38, v105, v105
	v_fmac_f32_e32 v38, v90, v90
	s_waitcnt lgkmcnt(3)
	v_add_f32_e32 v64, v102, v103
	global_load_dwordx4 v[90:93], v[34:35], off offset:256
	global_load_dwordx4 v[102:105], v[54:55], off offset:256
	global_load_dwordx2 v[62:63], v[174:175], off offset:1408
	v_add_f32_e32 v37, v38, v37
	v_mul_f32_e32 v38, v107, v107
	v_fmac_f32_e32 v38, v106, v106
	v_add_f32_e32 v37, v38, v37
	v_mul_f32_e32 v38, v57, v57
	v_mul_f32_e32 v39, v109, v109
	v_fmac_f32_e32 v38, v56, v56
	v_fmac_f32_e32 v39, v108, v108
	v_add_f32_e32 v38, v38, v39
	v_mul_f32_e32 v39, v111, v111
	v_fmac_f32_e32 v39, v110, v110
	v_add_f32_e32 v38, v39, v38
	v_mul_f32_e32 v39, v113, v113
	v_fmac_f32_e32 v39, v112, v112
	v_add_f32_e32 v38, v39, v38
	v_mul_f32_e32 v39, v43, v43
	v_mul_f32_e32 v40, v45, v45
	v_fmac_f32_e32 v39, v42, v42
	v_fmac_f32_e32 v40, v44, v44
	v_add_f32_e32 v39, v39, v40
	v_mul_f32_e32 v40, v47, v47
	v_fmac_f32_e32 v40, v46, v46
	v_add_f32_e32 v39, v40, v39
	v_mul_f32_e32 v40, v49, v49
	v_fmac_f32_e32 v40, v48, v48
	v_add_f32_e32 v39, v40, v39
	v_add_f32_e32 v36, v36, v37
	v_add_f32_e32 v38, v38, v39
	ds_bpermute_b32 v37, v129, v36
	ds_bpermute_b32 v39, v129, v38
	s_mov_b32 s8, 0xb0000
	v_add_co_u32_e32 v34, vcc, s8, v176
	s_waitcnt lgkmcnt(1)
	v_add_f32_e32 v66, v36, v37
	v_addc_co_u32_e32 v35, vcc, 0, v177, vcc
	v_add_co_u32_e32 v56, vcc, s8, v178
	s_waitcnt lgkmcnt(0)
	v_add_f32_e32 v68, v38, v39
	v_addc_co_u32_e32 v57, vcc, 0, v179, vcc
	global_load_dwordx4 v[46:49], v[34:35], off
	global_load_dwordx4 v[38:41], v[34:35], off offset:256
	global_load_dwordx4 v[42:45], v[56:57], off
	s_nop 0
	global_load_dwordx4 v[34:37], v[56:57], off offset:256
	global_store_dwordx4 v[86:87], v[58:61], off
	global_store_dwordx4 v[86:87], v[50:53], off offset:256
	global_store_dwordx4 v[88:89], v[74:77], off
	global_store_dwordx4 v[88:89], v[70:73], off offset:256
	v_mov_b32_e32 v51, v147
	ds_bpermute_b32 v65, v101, v64
	ds_bpermute_b32 v67, v101, v66
	ds_bpermute_b32 v69, v101, v68
	s_waitcnt vmcnt(13)
	v_mov_b32_e32 v50, v95
	v_lshlrev_b64 v[50:51], s2, v[50:51]
	v_min_u32_e32 v50, 1, v50
	v_or_b32_e32 v50, v51, v50
	v_cvt_f32_u32_e32 v52, v94
	v_cvt_f32_u32_e32 v50, v50
	v_fmamk_f32 v51, v52, 0x30000000, v209
	v_ldexp_f32 v50, v50, s12
	v_fmac_f32_e32 v51, 2.0, v50
	v_rsq_f32_e32 v50, v51
	s_waitcnt vmcnt(12)
	v_lshlrev_b32_e32 v59, 16, v80
	v_mul_f32_e32 v26, v26, v50
	v_mul_f32_e32 v26, 0xbfb8aa3b, v26
	v_exp_f32_e32 v26, v26
	v_mul_f32_e32 v27, v27, v50
	v_mul_f32_e32 v27, 0xbfb8aa3b, v27
	v_exp_f32_e32 v27, v27
	v_add_f32_e32 v26, 1.0, v26
	v_rcp_f32_e32 v26, v26
	s_waitcnt vmcnt(11)
	v_lshlrev_b32_e32 v75, 16, v84
	v_mul_f32_e32 v28, v28, v50
	v_mul_f32_e32 v28, 0xbfb8aa3b, v28
	v_fmac_f32_e32 v59, v26, v75
	v_add_f32_e32 v26, 1.0, v27
	v_mul_f32_e32 v27, v32, v50
	v_mul_f32_e32 v27, 0xbfb8aa3b, v27
	v_rcp_f32_e32 v26, v26
	v_exp_f32_e32 v27, v27
	v_exp_f32_e32 v28, v28
	v_and_b32_e32 v60, 0xffff0000, v80
	v_and_b32_e32 v76, 0xffff0000, v84
	v_mul_f32_e32 v31, v31, v50
	v_fmac_f32_e32 v60, v26, v76
	v_add_f32_e32 v26, 1.0, v27
	v_add_f32_e32 v27, 1.0, v28
	v_mul_f32_e32 v28, v33, v50
	v_mul_f32_e32 v30, v30, v50
	v_mul_f32_e32 v31, 0xbfb8aa3b, v31
	v_mul_f32_e32 v28, 0xbfb8aa3b, v28
	v_mul_f32_e32 v30, 0xbfb8aa3b, v30
	v_exp_f32_e32 v31, v31
	v_exp_f32_e32 v28, v28
	v_exp_f32_e32 v30, v30
	v_mul_f32_e32 v29, v29, v50
	v_mul_f32_e32 v29, 0xbfb8aa3b, v29
	v_add_f32_e32 v31, 1.0, v31
	v_exp_f32_e32 v29, v29
	v_add_f32_e32 v28, 1.0, v28
	v_add_f32_e32 v30, 1.0, v30
	v_rcp_f32_e32 v31, v31
	v_rcp_f32_e32 v28, v28
	v_rcp_f32_e32 v30, v30
	v_rcp_f32_e32 v26, v26
	v_rcp_f32_e32 v27, v27
	v_mul_f32_e32 v18, v18, v50
	v_mul_f32_e32 v18, 0xbfb8aa3b, v18
	v_and_b32_e32 v52, 0xffff0000, v78
	v_and_b32_e32 v58, 0xffff0000, v79
	v_and_b32_e32 v72, 0xffff0000, v82
	v_and_b32_e32 v74, 0xffff0000, v83
	v_add_f32_e32 v29, 1.0, v29
	v_exp_f32_e32 v18, v18
	v_lshlrev_b32_e32 v51, 16, v78
	v_lshlrev_b32_e32 v53, 16, v79
	v_lshlrev_b32_e32 v61, 16, v81
	v_lshlrev_b32_e32 v71, 16, v82
	v_lshlrev_b32_e32 v73, 16, v83
	v_lshlrev_b32_e32 v77, 16, v85
	v_fmac_f32_e32 v52, v31, v72
	v_rcp_f32_e32 v29, v29
	v_fmac_f32_e32 v58, v28, v74
	v_fmac_f32_e32 v51, v30, v71
	v_fmac_f32_e32 v53, v26, v73
	v_fmac_f32_e32 v61, v27, v77
	v_mul_f32_e32 v26, v52, v52
	v_mul_f32_e32 v27, v58, v58
	v_fmac_f32_e32 v26, v51, v51
	v_fmac_f32_e32 v27, v53, v53
	v_mul_f32_e32 v19, v19, v50
	v_and_b32_e32 v70, 0xffff0000, v81
	v_and_b32_e32 v78, 0xffff0000, v85
	v_add_f32_e32 v26, v26, v27
	v_mul_f32_e32 v27, v60, v60
	v_add_f32_e32 v18, 1.0, v18
	v_mul_f32_e32 v19, 0xbfb8aa3b, v19
	v_fmac_f32_e32 v70, v29, v78
	v_fmac_f32_e32 v27, v59, v59
	v_rcp_f32_e32 v18, v18
	v_exp_f32_e32 v19, v19
	v_add_f32_e32 v26, v27, v26
	v_mul_f32_e32 v27, v70, v70
	v_fmac_f32_e32 v27, v61, v61
	v_add_f32_e32 v30, v27, v26
	v_cvt_pk_bf16_f32 v26, v51, v52
	s_waitcnt vmcnt(10)
	v_lshlrev_b32_e32 v52, 16, v92
	s_waitcnt vmcnt(9)
	v_lshlrev_b32_e32 v72, 16, v104
	v_fmac_f32_e32 v52, v18, v72
	v_add_f32_e32 v18, 1.0, v19
	v_mul_f32_e32 v19, v24, v50
	v_mul_f32_e32 v20, v20, v50
	v_mul_f32_e32 v19, 0xbfb8aa3b, v19
	v_mul_f32_e32 v20, 0xbfb8aa3b, v20
	v_rcp_f32_e32 v18, v18
	v_exp_f32_e32 v19, v19
	v_exp_f32_e32 v20, v20
	v_cvt_pk_bf16_f32 v27, v53, v58
	v_and_b32_e32 v53, 0xffff0000, v92
	v_and_b32_e32 v73, 0xffff0000, v104
	v_mul_f32_e32 v23, v23, v50
	v_fmac_f32_e32 v53, v18, v73
	v_add_f32_e32 v18, 1.0, v19
	v_add_f32_e32 v19, 1.0, v20
	v_mul_f32_e32 v20, v25, v50
	v_mul_f32_e32 v22, v22, v50
	v_mul_f32_e32 v23, 0xbfb8aa3b, v23
	v_mul_f32_e32 v20, 0xbfb8aa3b, v20
	v_mul_f32_e32 v22, 0xbfb8aa3b, v22
	v_exp_f32_e32 v23, v23
	v_exp_f32_e32 v20, v20
	v_exp_f32_e32 v22, v22
	v_mul_f32_e32 v21, v21, v50
	v_mul_f32_e32 v21, 0xbfb8aa3b, v21
	v_add_f32_e32 v23, 1.0, v23
	v_exp_f32_e32 v21, v21
	v_add_f32_e32 v20, 1.0, v20
	v_add_f32_e32 v22, 1.0, v22
	v_rcp_f32_e32 v23, v23
	v_rcp_f32_e32 v20, v20
	v_rcp_f32_e32 v22, v22
	v_rcp_f32_e32 v18, v18
	v_rcp_f32_e32 v19, v19
	v_cvt_pk_bf16_f32 v28, v59, v60
	v_cvt_pk_bf16_f32 v29, v61, v70
	v_and_b32_e32 v32, 0xffff0000, v90
	v_and_b32_e32 v51, 0xffff0000, v91
	v_and_b32_e32 v61, 0xffff0000, v102
	v_and_b32_e32 v71, 0xffff0000, v103
	v_add_f32_e32 v21, 1.0, v21
	v_lshlrev_b32_e32 v31, 16, v90
	v_lshlrev_b32_e32 v33, 16, v91
	v_lshlrev_b32_e32 v58, 16, v93
	v_lshlrev_b32_e32 v60, 16, v102
	v_lshlrev_b32_e32 v70, 16, v103
	v_lshlrev_b32_e32 v74, 16, v105
	v_fmac_f32_e32 v32, v23, v61
	v_rcp_f32_e32 v21, v21
	v_fmac_f32_e32 v51, v20, v71
	v_fmac_f32_e32 v31, v22, v60
	v_fmac_f32_e32 v33, v18, v70
	v_fmac_f32_e32 v58, v19, v74
	v_mul_f32_e32 v18, v32, v32
	v_mul_f32_e32 v19, v51, v51
	v_fmac_f32_e32 v18, v31, v31
	v_fmac_f32_e32 v19, v33, v33
	v_and_b32_e32 v59, 0xffff0000, v93
	v_and_b32_e32 v75, 0xffff0000, v105
	v_add_f32_e32 v18, v18, v19
	v_mul_f32_e32 v19, v53, v53
	v_fmac_f32_e32 v59, v21, v75
	v_fmac_f32_e32 v19, v52, v52
	v_add_f32_e32 v18, v19, v18
	v_mul_f32_e32 v19, v59, v59
	v_fmac_f32_e32 v19, v58, v58
	s_waitcnt vmcnt(8)
	v_mov_b32_e32 v22, v63
	v_mov_b32_e32 v23, v147
	v_add_f32_e32 v18, v19, v18
	v_mov_b32_e32 v23, v22
	v_add_f32_e32 v24, v30, v18
	ds_bpermute_b32 v25, v129, v24
	v_cvt_pk_bf16_f32 v18, v31, v32
	v_cvt_f32_u32_e32 v30, v62
	v_cvt_f32_u32_e32 v31, v23
	s_waitcnt lgkmcnt(0)
	v_add_f32_e32 v22, v24, v25
	v_cvt_pk_bf16_f32 v19, v33, v51
	v_fmamk_f32 v24, v30, 0x30000000, v209
	v_mov_b32_e32 v25, v31
	v_fmac_f32_e32 v24, 2.0, v25
	v_rsq_f32_e32 v24, v24
	s_waitcnt vmcnt(7)
	v_lshlrev_b32_e32 v33, 16, v48
	s_waitcnt vmcnt(5)
	v_lshlrev_b32_e32 v51, 16, v44
	v_lshlrev_b32_e32 v25, 16, v46
	v_mul_f32_e32 v10, v10, v24
	v_mul_f32_e32 v10, 0xbfb8aa3b, v10
	v_exp_f32_e32 v10, v10
	v_mul_f32_e32 v11, v11, v24
	v_mul_f32_e32 v11, 0xbfb8aa3b, v11
	v_exp_f32_e32 v11, v11
	v_add_f32_e32 v10, 1.0, v10
	v_rcp_f32_e32 v10, v10
	v_mul_f32_e32 v12, v12, v24
	v_mul_f32_e32 v12, 0xbfb8aa3b, v12
	v_exp_f32_e32 v12, v12
	v_fmac_f32_e32 v33, v10, v51
	v_add_f32_e32 v10, 1.0, v11
	v_mul_f32_e32 v11, v16, v24
	v_mul_f32_e32 v11, 0xbfb8aa3b, v11
	v_rcp_f32_e32 v10, v10
	v_exp_f32_e32 v11, v11
	v_and_b32_e32 v30, 0xffff0000, v46
	v_and_b32_e32 v46, 0xffff0000, v48
	v_and_b32_e32 v44, 0xffff0000, v44
	v_mul_f32_e32 v15, v15, v24
	v_fmac_f32_e32 v46, v10, v44
	v_add_f32_e32 v10, 1.0, v11
	v_add_f32_e32 v11, 1.0, v12
	v_mul_f32_e32 v12, v17, v24
	v_mul_f32_e32 v14, v14, v24
	v_mul_f32_e32 v15, 0xbfb8aa3b, v15
	v_mul_f32_e32 v12, 0xbfb8aa3b, v12
	v_mul_f32_e32 v14, 0xbfb8aa3b, v14
	v_exp_f32_e32 v15, v15
	v_exp_f32_e32 v12, v12
	v_exp_f32_e32 v14, v14
	v_mul_f32_e32 v13, v13, v24
	v_mul_f32_e32 v13, 0xbfb8aa3b, v13
	v_add_f32_e32 v15, 1.0, v15
	v_exp_f32_e32 v13, v13
	v_add_f32_e32 v12, 1.0, v12
	v_add_f32_e32 v14, 1.0, v14
	v_rcp_f32_e32 v15, v15
	v_rcp_f32_e32 v12, v12
	v_rcp_f32_e32 v14, v14
	v_rcp_f32_e32 v10, v10
	v_rcp_f32_e32 v11, v11
	v_mul_f32_e32 v2, v2, v24
	v_mul_f32_e32 v2, 0xbfb8aa3b, v2
	v_lshlrev_b32_e32 v31, 16, v47
	v_and_b32_e32 v32, 0xffff0000, v47
	v_lshlrev_b32_e32 v47, 16, v49
	v_and_b32_e32 v48, 0xffff0000, v49
	v_lshlrev_b32_e32 v49, 16, v42
	v_and_b32_e32 v42, 0xffff0000, v42
	v_lshlrev_b32_e32 v50, 16, v43
	v_and_b32_e32 v43, 0xffff0000, v43
	v_add_f32_e32 v13, 1.0, v13
	v_exp_f32_e32 v2, v2
	v_cvt_pk_bf16_f32 v20, v52, v53
	v_lshlrev_b32_e32 v52, 16, v45
	v_fmac_f32_e32 v30, v15, v42
	v_rcp_f32_e32 v13, v13
	v_fmac_f32_e32 v32, v12, v43
	v_fmac_f32_e32 v25, v14, v49
	v_fmac_f32_e32 v31, v10, v50
	v_fmac_f32_e32 v47, v11, v52
	v_mul_f32_e32 v10, v30, v30
	v_mul_f32_e32 v11, v32, v32
	v_fmac_f32_e32 v10, v25, v25
	v_fmac_f32_e32 v11, v31, v31
	v_mul_f32_e32 v3, v3, v24
	v_and_b32_e32 v45, 0xffff0000, v45
	v_add_f32_e32 v10, v10, v11
	v_mul_f32_e32 v11, v46, v46
	v_add_f32_e32 v2, 1.0, v2
	v_mul_f32_e32 v3, 0xbfb8aa3b, v3
	v_fmac_f32_e32 v48, v13, v45
	v_fmac_f32_e32 v11, v33, v33
	v_rcp_f32_e32 v2, v2
	v_exp_f32_e32 v3, v3
	v_add_f32_e32 v10, v11, v10
	v_mul_f32_e32 v11, v48, v48
	v_fmac_f32_e32 v11, v47, v47
	v_cvt_pk_bf16_f32 v21, v58, v59
	v_add_f32_e32 v14, v11, v10
	v_cvt_pk_bf16_f32 v10, v25, v30
	v_cvt_pk_bf16_f32 v11, v31, v32
	v_lshlrev_b32_e32 v30, 16, v40
	v_and_b32_e32 v31, 0xffff0000, v40
	s_waitcnt vmcnt(4)
	v_lshlrev_b32_e32 v40, 16, v36
	v_fmac_f32_e32 v30, v2, v40
	v_add_f32_e32 v2, 1.0, v3
	v_mul_f32_e32 v3, v8, v24
	v_mul_f32_e32 v4, v4, v24
	v_mul_f32_e32 v3, 0xbfb8aa3b, v3
	v_mul_f32_e32 v4, 0xbfb8aa3b, v4
	v_rcp_f32_e32 v2, v2
	v_exp_f32_e32 v3, v3
	v_exp_f32_e32 v4, v4
	v_and_b32_e32 v36, 0xffff0000, v36
	v_mul_f32_e32 v7, v7, v24
	v_fmac_f32_e32 v31, v2, v36
	v_add_f32_e32 v2, 1.0, v3
	v_add_f32_e32 v3, 1.0, v4
	v_mul_f32_e32 v4, v9, v24
	v_mul_f32_e32 v6, v6, v24
	v_mul_f32_e32 v7, 0xbfb8aa3b, v7
	v_mul_f32_e32 v4, 0xbfb8aa3b, v4
	v_mul_f32_e32 v6, 0xbfb8aa3b, v6
	v_exp_f32_e32 v7, v7
	v_exp_f32_e32 v4, v4
	v_exp_f32_e32 v6, v6
	v_mul_f32_e32 v5, v5, v24
	v_mul_f32_e32 v5, 0xbfb8aa3b, v5
	v_add_f32_e32 v7, 1.0, v7
	v_exp_f32_e32 v5, v5
	v_add_f32_e32 v4, 1.0, v4
	v_add_f32_e32 v6, 1.0, v6
	v_rcp_f32_e32 v7, v7
	v_rcp_f32_e32 v4, v4
	v_rcp_f32_e32 v6, v6
	v_rcp_f32_e32 v2, v2
	v_rcp_f32_e32 v3, v3
	v_lshlrev_b32_e32 v15, 16, v38
	v_and_b32_e32 v16, 0xffff0000, v38
	v_lshlrev_b32_e32 v17, 16, v39
	v_and_b32_e32 v25, 0xffff0000, v39
	v_lshlrev_b32_e32 v38, 16, v34
	v_and_b32_e32 v34, 0xffff0000, v34
	v_lshlrev_b32_e32 v39, 16, v35
	v_and_b32_e32 v35, 0xffff0000, v35
	v_add_f32_e32 v5, 1.0, v5
	v_cvt_pk_bf16_f32 v12, v33, v46
	v_lshlrev_b32_e32 v32, 16, v41
	v_and_b32_e32 v33, 0xffff0000, v41
	v_lshlrev_b32_e32 v41, 16, v37
	v_fmac_f32_e32 v16, v7, v34
	v_rcp_f32_e32 v5, v5
	v_fmac_f32_e32 v25, v4, v35
	v_fmac_f32_e32 v15, v6, v38
	v_fmac_f32_e32 v17, v2, v39
	v_fmac_f32_e32 v32, v3, v41
	v_mul_f32_e32 v2, v16, v16
	v_mul_f32_e32 v3, v25, v25
	v_fmac_f32_e32 v2, v15, v15
	v_fmac_f32_e32 v3, v17, v17
	v_and_b32_e32 v37, 0xffff0000, v37
	v_add_f32_e32 v2, v2, v3
	v_mul_f32_e32 v3, v31, v31
	v_fmac_f32_e32 v33, v5, v37
	v_fmac_f32_e32 v3, v30, v30
	v_add_f32_e32 v2, v3, v2
	v_mul_f32_e32 v3, v33, v33
	v_fmac_f32_e32 v3, v32, v32
	v_add_f32_e32 v2, v3, v2
	v_add_f32_e32 v2, v14, v2
	ds_bpermute_b32 v3, v129, v2
	ds_bpermute_b32 v23, v101, v22
	v_cvt_pk_bf16_f32 v13, v47, v48
	v_cvt_pk_bf16_f32 v4, v15, v16
	v_cvt_pk_bf16_f32 v5, v17, v25
	s_waitcnt lgkmcnt(1)
	v_add_f32_e32 v2, v2, v3
	ds_bpermute_b32 v3, v101, v2
	v_cvt_pk_bf16_f32 v6, v30, v31
	v_cvt_pk_bf16_f32 v7, v32, v33
	global_store_dwordx4 v[54:55], v[26:29], off
	global_store_dwordx4 v[54:55], v[18:21], off offset:256
	global_store_dwordx4 v[56:57], v[10:13], off
	global_store_dwordx4 v[56:57], v[4:7], off offset:256
	s_and_saveexec_b64 s[8:9], s[38:39]
	s_cbranch_execz .LBB0_2455
	v_add_f32_e32 v4, v128, v96
	v_fma_f32 v4, v4, s11, 0.5
	v_trunc_f32_e32 v4, v4
	v_mul_f32_e32 v5, 0x2f800000, v4
	v_floor_f32_e32 v5, v5
	v_fmac_f32_e32 v4, 0xcf800000, v5
	v_cvt_u32_f32_e32 v4, v4
	v_cvt_u32_f32_e32 v5, v5
	s_waitcnt lgkmcnt(0)
	v_add_f32_e32 v6, v2, v3
	v_add_f32_e32 v12, v97, v98
	v_lshl_add_u64 v[2:3], s[24:25], 3, v[172:173]
	global_atomic_add_x2 v[2:3], v[4:5], off
	v_fma_f32 v4, v12, s11, 0.5
	v_trunc_f32_e32 v4, v4
	v_mul_f32_e32 v5, 0x2f800000, v4
	v_floor_f32_e32 v5, v5
	v_fmac_f32_e32 v4, 0xcf800000, v5
	v_cvt_u32_f32_e32 v4, v4
	v_cvt_u32_f32_e32 v5, v5
	v_add_f32_e32 v11, v99, v100
	v_add_f32_e32 v10, v64, v65
	v_add_f32_e32 v9, v66, v67
	global_atomic_add_x2 v[2:3], v[4:5], off offset:128
	v_fma_f32 v4, v11, s11, 0.5
	v_trunc_f32_e32 v4, v4
	v_mul_f32_e32 v5, 0x2f800000, v4
	v_floor_f32_e32 v5, v5
	v_fmac_f32_e32 v4, 0xcf800000, v5
	v_cvt_u32_f32_e32 v4, v4
	v_cvt_u32_f32_e32 v5, v5
	v_add_f32_e32 v8, v68, v69
	v_add_f32_e32 v7, v22, v23
	global_atomic_add_x2 v[2:3], v[4:5], off offset:256
	v_fma_f32 v4, v10, s11, 0.5
	v_trunc_f32_e32 v4, v4
	v_mul_f32_e32 v5, 0x2f800000, v4
	v_floor_f32_e32 v5, v5
	v_fmac_f32_e32 v4, 0xcf800000, v5
	v_cvt_u32_f32_e32 v4, v4
	v_cvt_u32_f32_e32 v5, v5
	global_atomic_add_x2 v[2:3], v[4:5], off offset:384
	v_fma_f32 v4, v9, s11, 0.5
	v_trunc_f32_e32 v4, v4
	v_mul_f32_e32 v5, 0x2f800000, v4
	v_floor_f32_e32 v5, v5
	v_fmac_f32_e32 v4, 0xcf800000, v5
	v_cvt_u32_f32_e32 v4, v4
	v_cvt_u32_f32_e32 v5, v5
	global_atomic_add_x2 v[2:3], v[4:5], off offset:1024
	v_fma_f32 v4, v8, s11, 0.5
	v_trunc_f32_e32 v4, v4
	v_mul_f32_e32 v5, 0x2f800000, v4
	v_floor_f32_e32 v5, v5
	v_fmac_f32_e32 v4, 0xcf800000, v5
	v_cvt_u32_f32_e32 v4, v4
	v_cvt_u32_f32_e32 v5, v5
	global_atomic_add_x2 v[2:3], v[4:5], off offset:1152
	v_fma_f32 v4, v7, s11, 0.5
	v_trunc_f32_e32 v4, v4
	v_mul_f32_e32 v5, 0x2f800000, v4
	v_floor_f32_e32 v5, v5
	v_fmac_f32_e32 v4, 0xcf800000, v5
	v_cvt_u32_f32_e32 v4, v4
	v_cvt_u32_f32_e32 v5, v5
	global_atomic_add_x2 v[2:3], v[4:5], off offset:1280
	v_fma_f32 v4, v6, s11, 0.5
	v_trunc_f32_e32 v4, v4
	v_mul_f32_e32 v5, 0x2f800000, v4
	v_floor_f32_e32 v5, v5
	v_fmac_f32_e32 v4, 0xcf800000, v5
	v_cvt_u32_f32_e32 v4, v4
	v_cvt_u32_f32_e32 v5, v5
	global_atomic_add_x2 v[2:3], v[4:5], off offset:1408
